# nt_stores_inproj_scin
# speedup vs baseline: 1.0470x; 1.0003x over previous
.LBB0_150:
	ds_read_b128 v[152:155], v148
	ds_read_b128 v[156:159], v148 offset:1024
	ds_read_b128 v[160:163], v148 offset:2048
	ds_read_b128 v[164:167], v148 offset:3072
	s_add_u32 s40, s38, 0xfffc0080
	s_addc_u32 s41, s39, -1
	s_cmp_eq_u32 s75, 12
	s_cselect_b32 s43, s13, s41
	s_cselect_b32 s42, s37, s40
	s_cselect_b32 s41, s9, s74
	s_cselect_b32 s40, s72, s73
	v_lshl_add_u64 v[200:201], s[38:39], 0, v[136:137]
	s_add_i32 m0, s51, 0xc000
	ds_read_b128 v[168:171], v149
	ds_read_b128 v[172:175], v149 offset:1024
	ds_read_b128 v[176:179], v149 offset:2048
	ds_read_b128 v[180:183], v149 offset:3072
	ds_read_b128 v[184:187], v149 offset:4096
	ds_read_b128 v[188:191], v149 offset:5120
	ds_read_b128 v[192:195], v149 offset:6144
	ds_read_b128 v[196:199], v149 offset:7168
	global_load_lds_dwordx4 v[200:201], off
	v_lshl_add_u64 v[200:201], s[38:39], 0, v[138:139]
	s_add_i32 m0, s51, 0xe000
	s_nop 0
	global_load_lds_dwordx4 v[200:201], off
	s_waitcnt lgkmcnt(8)
	s_barrier
	s_waitcnt lgkmcnt(0)
	s_setprio 1
	s_waitcnt lgkmcnt(0)
	v_mfma_f32_16x16x32_bf16 v[124:127], v[152:155], v[168:171], v[124:127]
	v_mfma_f32_16x16x32_bf16 v[120:123], v[160:163], v[168:171], v[120:123]
	v_mfma_f32_16x16x32_bf16 v[116:119], v[152:155], v[176:179], v[116:119]
	v_mfma_f32_16x16x32_bf16 v[112:115], v[160:163], v[176:179], v[112:115]
	v_mfma_f32_16x16x32_bf16 v[108:111], v[152:155], v[184:187], v[108:111]
	v_mfma_f32_16x16x32_bf16 v[104:107], v[160:163], v[184:187], v[104:107]
	v_mfma_f32_16x16x32_bf16 v[100:103], v[152:155], v[192:195], v[100:103]
	v_mfma_f32_16x16x32_bf16 v[96:99], v[160:163], v[192:195], v[96:99]
	v_mfma_f32_16x16x32_bf16 v[124:127], v[156:159], v[172:175], v[124:127]
	v_mfma_f32_16x16x32_bf16 v[120:123], v[164:167], v[172:175], v[120:123]
	v_mfma_f32_16x16x32_bf16 v[116:119], v[156:159], v[180:183], v[116:119]
	v_mfma_f32_16x16x32_bf16 v[112:115], v[164:167], v[180:183], v[112:115]
	v_mfma_f32_16x16x32_bf16 v[108:111], v[156:159], v[188:191], v[108:111]
	v_mfma_f32_16x16x32_bf16 v[104:107], v[164:167], v[188:191], v[104:107]
	v_mfma_f32_16x16x32_bf16 v[100:103], v[156:159], v[196:199], v[100:103]
	v_mfma_f32_16x16x32_bf16 v[96:99], v[164:167], v[196:199], v[96:99]
	s_setprio 0
	s_barrier
	s_add_i32 s76, s69, s48
	v_lshl_add_u64 v[208:209], s[40:41], 0, v[132:133]
	s_mov_b32 m0, s76
	ds_read_b128 v[200:203], v150
	ds_read_b128 v[204:207], v150 offset:1024
	ds_read_b128 v[212:215], v150 offset:2048
	ds_read_b128 v[216:219], v150 offset:3072
	global_load_lds_dwordx4 v[208:209], off
	v_lshl_add_u64 v[220:221], s[40:41], 0, v[128:129]
	s_add_i32 m0, s76, 0x2000
	s_nop 0
	global_load_lds_dwordx4 v[220:221], off
	s_barrier
	s_waitcnt lgkmcnt(0)
	s_setprio 1
	s_waitcnt lgkmcnt(0)
	v_mfma_f32_16x16x32_bf16 v[76:79], v[200:203], v[168:171], v[76:79]
	v_mfma_f32_16x16x32_bf16 v[72:75], v[212:215], v[168:171], v[72:75]
	v_mfma_f32_16x16x32_bf16 v[60:63], v[200:203], v[176:179], v[60:63]
	v_mfma_f32_16x16x32_bf16 v[56:59], v[212:215], v[176:179], v[56:59]
	v_mfma_f32_16x16x32_bf16 v[44:47], v[200:203], v[184:187], v[44:47]
	v_mfma_f32_16x16x32_bf16 v[40:43], v[212:215], v[184:187], v[40:43]
	v_mfma_f32_16x16x32_bf16 v[36:39], v[200:203], v[192:195], v[36:39]
	v_mfma_f32_16x16x32_bf16 v[32:35], v[212:215], v[192:195], v[32:35]
	v_mfma_f32_16x16x32_bf16 v[76:79], v[204:207], v[172:175], v[76:79]
	v_mfma_f32_16x16x32_bf16 v[72:75], v[216:219], v[172:175], v[72:75]
	v_mfma_f32_16x16x32_bf16 v[60:63], v[204:207], v[180:183], v[60:63]
	v_mfma_f32_16x16x32_bf16 v[56:59], v[216:219], v[180:183], v[56:59]
	v_mfma_f32_16x16x32_bf16 v[44:47], v[204:207], v[188:191], v[44:47]
	v_mfma_f32_16x16x32_bf16 v[40:43], v[216:219], v[188:191], v[40:43]
	v_mfma_f32_16x16x32_bf16 v[36:39], v[204:207], v[196:199], v[36:39]
	v_mfma_f32_16x16x32_bf16 v[32:35], v[216:219], v[196:199], v[32:35]
	s_setprio 0
	s_mov_b32 m0, s51
	v_lshl_add_u64 v[222:223], s[42:43], 0, v[134:135]
	s_barrier
	ds_read_b128 v[168:171], v149 offset:16384
	ds_read_b128 v[172:175], v149 offset:17408
	ds_read_b128 v[176:179], v149 offset:18432
	ds_read_b128 v[180:183], v149 offset:19456
	ds_read_b128 v[184:187], v149 offset:20480
	ds_read_b128 v[188:191], v149 offset:21504
	ds_read_b128 v[192:195], v149 offset:22528
	ds_read_b128 v[196:199], v149 offset:23552
	global_load_lds_dwordx4 v[222:223], off
	v_lshl_add_u64 v[224:225], s[42:43], 0, v[130:131]
	s_mov_b32 m0, s54
	s_nop 0
	global_load_lds_dwordx4 v[224:225], off
	s_barrier
	s_waitcnt lgkmcnt(0)
	s_setprio 1
	s_waitcnt lgkmcnt(0)
	v_mfma_f32_16x16x32_bf16 v[92:95], v[152:155], v[168:171], v[92:95]
	v_mfma_f32_16x16x32_bf16 v[88:91], v[160:163], v[168:171], v[88:91]
	v_mfma_f32_16x16x32_bf16 v[84:87], v[152:155], v[176:179], v[84:87]
	v_mfma_f32_16x16x32_bf16 v[80:83], v[160:163], v[176:179], v[80:83]
	v_mfma_f32_16x16x32_bf16 v[68:71], v[152:155], v[184:187], v[68:71]
	v_mfma_f32_16x16x32_bf16 v[64:67], v[160:163], v[184:187], v[64:67]
	v_mfma_f32_16x16x32_bf16 v[52:55], v[152:155], v[192:195], v[52:55]
	v_mfma_f32_16x16x32_bf16 v[48:51], v[160:163], v[192:195], v[48:51]
	v_mfma_f32_16x16x32_bf16 v[92:95], v[156:159], v[172:175], v[92:95]
	v_mfma_f32_16x16x32_bf16 v[88:91], v[164:167], v[172:175], v[88:91]
	v_mfma_f32_16x16x32_bf16 v[84:87], v[156:159], v[180:183], v[84:87]
	v_mfma_f32_16x16x32_bf16 v[80:83], v[164:167], v[180:183], v[80:83]
	v_mfma_f32_16x16x32_bf16 v[68:71], v[156:159], v[188:191], v[68:71]
	v_mfma_f32_16x16x32_bf16 v[64:67], v[164:167], v[188:191], v[64:67]
	v_mfma_f32_16x16x32_bf16 v[52:55], v[156:159], v[196:199], v[52:55]
	v_mfma_f32_16x16x32_bf16 v[48:51], v[164:167], v[196:199], v[48:51]
	s_setprio 0
	s_barrier
	s_add_u32 s76, s40, 0x40000
	s_addc_u32 s77, s41, 0
	s_add_i32 s78, s70, s48
	v_lshl_add_u64 v[152:153], s[76:77], 0, v[132:133]
	s_mov_b32 m0, s78
	s_nop 0
	global_load_lds_dwordx4 v[152:153], off
	v_lshl_add_u64 v[152:153], s[76:77], 0, v[128:129]
	s_add_i32 m0, s78, 0x2000
	s_nop 0
	global_load_lds_dwordx4 v[152:153], off
	s_waitcnt vmcnt(6)
	s_barrier
	s_setprio 1
	v_mfma_f32_16x16x32_bf16 v[28:31], v[200:203], v[168:171], v[28:31]
	v_mfma_f32_16x16x32_bf16 v[24:27], v[212:215], v[168:171], v[24:27]
	v_mfma_f32_16x16x32_bf16 v[20:23], v[200:203], v[176:179], v[20:23]
	v_mfma_f32_16x16x32_bf16 v[16:19], v[212:215], v[176:179], v[16:19]
	v_mfma_f32_16x16x32_bf16 v[12:15], v[200:203], v[184:187], v[12:15]
	v_mfma_f32_16x16x32_bf16 v[8:11], v[212:215], v[184:187], v[8:11]
	v_mfma_f32_16x16x32_bf16 v[4:7], v[200:203], v[192:195], v[4:7]
	v_mfma_f32_16x16x32_bf16 v[0:3], v[212:215], v[192:195], v[0:3]
	v_mfma_f32_16x16x32_bf16 v[28:31], v[204:207], v[172:175], v[28:31]
	v_mfma_f32_16x16x32_bf16 v[24:27], v[216:219], v[172:175], v[24:27]
	v_mfma_f32_16x16x32_bf16 v[20:23], v[204:207], v[180:183], v[20:23]
	v_mfma_f32_16x16x32_bf16 v[16:19], v[216:219], v[180:183], v[16:19]
	v_mfma_f32_16x16x32_bf16 v[12:15], v[204:207], v[188:191], v[12:15]
	v_mfma_f32_16x16x32_bf16 v[8:11], v[216:219], v[188:191], v[8:11]
	v_mfma_f32_16x16x32_bf16 v[4:7], v[204:207], v[196:199], v[4:7]
	v_mfma_f32_16x16x32_bf16 v[0:3], v[216:219], v[196:199], v[0:3]
	s_setprio 0
	s_add_i32 s76, 0, 0x18000
	v_add_u32_e32 v151, s76, v146
	s_barrier
	ds_read_b128 v[152:155], v151
	ds_read_b128 v[156:159], v151 offset:1024
	ds_read_b128 v[160:163], v151 offset:2048
	ds_read_b128 v[164:167], v151 offset:3072
	s_add_u32 s42, s42, 0x40000
	s_addc_u32 s43, s43, 0
	s_mov_b32 m0, s55
	v_lshl_add_u64 v[200:201], s[42:43], 0, v[134:135]
	ds_read_b128 v[168:171], v149 offset:32768
	ds_read_b128 v[172:175], v149 offset:33792
	ds_read_b128 v[176:179], v149 offset:34816
	ds_read_b128 v[180:183], v149 offset:35840
	ds_read_b128 v[184:187], v149 offset:36864
	ds_read_b128 v[188:191], v149 offset:37888
	ds_read_b128 v[192:195], v149 offset:38912
	ds_read_b128 v[196:199], v149 offset:39936
	global_load_lds_dwordx4 v[200:201], off
	v_lshl_add_u64 v[200:201], s[42:43], 0, v[130:131]
	s_mov_b32 m0, s62
	s_nop 0
	global_load_lds_dwordx4 v[200:201], off
	s_waitcnt lgkmcnt(8)
	s_barrier
	s_waitcnt lgkmcnt(0)
	s_setprio 1
	s_waitcnt lgkmcnt(0)
	v_mfma_f32_16x16x32_bf16 v[124:127], v[152:155], v[168:171], v[124:127]
	v_mfma_f32_16x16x32_bf16 v[120:123], v[160:163], v[168:171], v[120:123]
	v_mfma_f32_16x16x32_bf16 v[116:119], v[152:155], v[176:179], v[116:119]
	v_mfma_f32_16x16x32_bf16 v[112:115], v[160:163], v[176:179], v[112:115]
	v_mfma_f32_16x16x32_bf16 v[108:111], v[152:155], v[184:187], v[108:111]
	v_mfma_f32_16x16x32_bf16 v[104:107], v[160:163], v[184:187], v[104:107]
	v_mfma_f32_16x16x32_bf16 v[100:103], v[152:155], v[192:195], v[100:103]
	v_mfma_f32_16x16x32_bf16 v[96:99], v[160:163], v[192:195], v[96:99]
	v_mfma_f32_16x16x32_bf16 v[124:127], v[156:159], v[172:175], v[124:127]
	v_mfma_f32_16x16x32_bf16 v[120:123], v[164:167], v[172:175], v[120:123]
	v_mfma_f32_16x16x32_bf16 v[116:119], v[156:159], v[180:183], v[116:119]
	v_mfma_f32_16x16x32_bf16 v[112:115], v[164:167], v[180:183], v[112:115]
	v_mfma_f32_16x16x32_bf16 v[108:111], v[156:159], v[188:191], v[108:111]
	v_mfma_f32_16x16x32_bf16 v[104:107], v[164:167], v[188:191], v[104:107]
	v_mfma_f32_16x16x32_bf16 v[100:103], v[156:159], v[196:199], v[100:103]
	v_mfma_f32_16x16x32_bf16 v[96:99], v[164:167], v[196:199], v[96:99]
	s_setprio 0
	s_barrier
	s_add_i32 s42, 0, 0x1c000
	s_add_i32 s43, s76, s48
	v_add_u32_e32 v151, s42, v146
	v_lshl_add_u64 v[208:209], v[208:209], 0, s[0:1]
	s_mov_b32 m0, s43
	ds_read_b128 v[200:203], v151
	ds_read_b128 v[204:207], v151 offset:1024
	ds_read_b128 v[212:215], v151 offset:2048
	ds_read_b128 v[216:219], v151 offset:3072
	global_load_lds_dwordx4 v[208:209], off
	v_lshl_add_u64 v[208:209], v[220:221], 0, s[0:1]
	s_add_i32 m0, s43, 0x2000
	s_nop 0
	global_load_lds_dwordx4 v[208:209], off
	s_barrier
	s_waitcnt lgkmcnt(0)
	s_setprio 1
	s_waitcnt lgkmcnt(0)
	v_mfma_f32_16x16x32_bf16 v[76:79], v[200:203], v[168:171], v[76:79]
	v_mfma_f32_16x16x32_bf16 v[72:75], v[212:215], v[168:171], v[72:75]
	v_mfma_f32_16x16x32_bf16 v[60:63], v[200:203], v[176:179], v[60:63]
	v_mfma_f32_16x16x32_bf16 v[56:59], v[212:215], v[176:179], v[56:59]
	v_mfma_f32_16x16x32_bf16 v[44:47], v[200:203], v[184:187], v[44:47]
	v_mfma_f32_16x16x32_bf16 v[40:43], v[212:215], v[184:187], v[40:43]
	v_mfma_f32_16x16x32_bf16 v[36:39], v[200:203], v[192:195], v[36:39]
	v_mfma_f32_16x16x32_bf16 v[32:35], v[212:215], v[192:195], v[32:35]
	v_mfma_f32_16x16x32_bf16 v[76:79], v[204:207], v[172:175], v[76:79]
	v_mfma_f32_16x16x32_bf16 v[72:75], v[216:219], v[172:175], v[72:75]
	v_mfma_f32_16x16x32_bf16 v[60:63], v[204:207], v[180:183], v[60:63]
	v_mfma_f32_16x16x32_bf16 v[56:59], v[216:219], v[180:183], v[56:59]
	v_mfma_f32_16x16x32_bf16 v[44:47], v[204:207], v[188:191], v[44:47]
	v_mfma_f32_16x16x32_bf16 v[40:43], v[216:219], v[188:191], v[40:43]
	v_mfma_f32_16x16x32_bf16 v[36:39], v[204:207], v[196:199], v[36:39]
	v_mfma_f32_16x16x32_bf16 v[32:35], v[216:219], v[196:199], v[32:35]
	s_setprio 0
	s_mov_b32 m0, s63
	v_lshl_add_u64 v[208:209], v[222:223], 0, s[0:1]
	s_barrier
	ds_read_b128 v[168:171], v149 offset:49152
	ds_read_b128 v[172:175], v149 offset:50176
	ds_read_b128 v[176:179], v149 offset:51200
	ds_read_b128 v[180:183], v149 offset:52224
	ds_read_b128 v[184:187], v149 offset:53248
	ds_read_b128 v[188:191], v149 offset:54272
	ds_read_b128 v[192:195], v149 offset:55296
	ds_read_b128 v[196:199], v149 offset:56320
	global_load_lds_dwordx4 v[208:209], off
	v_lshl_add_u64 v[208:209], v[224:225], 0, s[0:1]
	s_mov_b32 m0, s64
	s_nop 0
	global_load_lds_dwordx4 v[208:209], off
	s_barrier
	s_waitcnt lgkmcnt(0)
	s_setprio 1
	s_waitcnt lgkmcnt(0)
	v_mfma_f32_16x16x32_bf16 v[92:95], v[152:155], v[168:171], v[92:95]
	v_mfma_f32_16x16x32_bf16 v[88:91], v[160:163], v[168:171], v[88:91]
	v_mfma_f32_16x16x32_bf16 v[84:87], v[152:155], v[176:179], v[84:87]
	v_mfma_f32_16x16x32_bf16 v[80:83], v[160:163], v[176:179], v[80:83]
	v_mfma_f32_16x16x32_bf16 v[68:71], v[152:155], v[184:187], v[68:71]
	v_mfma_f32_16x16x32_bf16 v[64:67], v[160:163], v[184:187], v[64:67]
	v_mfma_f32_16x16x32_bf16 v[52:55], v[152:155], v[192:195], v[52:55]
	v_mfma_f32_16x16x32_bf16 v[48:51], v[160:163], v[192:195], v[48:51]
	v_mfma_f32_16x16x32_bf16 v[92:95], v[156:159], v[172:175], v[92:95]
	v_mfma_f32_16x16x32_bf16 v[88:91], v[164:167], v[172:175], v[88:91]
	v_mfma_f32_16x16x32_bf16 v[84:87], v[156:159], v[180:183], v[84:87]
	v_mfma_f32_16x16x32_bf16 v[80:83], v[164:167], v[180:183], v[80:83]
	v_mfma_f32_16x16x32_bf16 v[68:71], v[156:159], v[188:191], v[68:71]
	v_mfma_f32_16x16x32_bf16 v[64:67], v[164:167], v[188:191], v[64:67]
	v_mfma_f32_16x16x32_bf16 v[52:55], v[156:159], v[196:199], v[52:55]
	v_mfma_f32_16x16x32_bf16 v[48:51], v[164:167], v[196:199], v[48:51]
	s_setprio 0
	s_barrier
	s_add_u32 s40, s40, 0x40080
	s_addc_u32 s41, s41, 0
	s_add_i32 s42, s42, s48
	v_lshl_add_u64 v[152:153], s[40:41], 0, v[132:133]
	s_mov_b32 m0, s42
	s_nop 0
	global_load_lds_dwordx4 v[152:153], off
	v_lshl_add_u64 v[152:153], s[40:41], 0, v[128:129]
	s_add_i32 m0, s42, 0x2000
	s_nop 0
	global_load_lds_dwordx4 v[152:153], off
	s_waitcnt vmcnt(6)
	s_barrier
	s_setprio 1
	v_mfma_f32_16x16x32_bf16 v[28:31], v[200:203], v[168:171], v[28:31]
	v_mfma_f32_16x16x32_bf16 v[24:27], v[212:215], v[168:171], v[24:27]
	v_mfma_f32_16x16x32_bf16 v[20:23], v[200:203], v[176:179], v[20:23]
	v_mfma_f32_16x16x32_bf16 v[16:19], v[212:215], v[176:179], v[16:19]
	v_mfma_f32_16x16x32_bf16 v[12:15], v[200:203], v[184:187], v[12:15]
	v_mfma_f32_16x16x32_bf16 v[8:11], v[212:215], v[184:187], v[8:11]
	v_mfma_f32_16x16x32_bf16 v[4:7], v[200:203], v[192:195], v[4:7]
	v_mfma_f32_16x16x32_bf16 v[0:3], v[212:215], v[192:195], v[0:3]
	v_mfma_f32_16x16x32_bf16 v[28:31], v[204:207], v[172:175], v[28:31]
	v_mfma_f32_16x16x32_bf16 v[24:27], v[216:219], v[172:175], v[24:27]
	v_mfma_f32_16x16x32_bf16 v[20:23], v[204:207], v[180:183], v[20:23]
	v_mfma_f32_16x16x32_bf16 v[16:19], v[216:219], v[180:183], v[16:19]
	v_mfma_f32_16x16x32_bf16 v[12:15], v[204:207], v[188:191], v[12:15]
	v_mfma_f32_16x16x32_bf16 v[8:11], v[216:219], v[188:191], v[8:11]
	v_mfma_f32_16x16x32_bf16 v[4:7], v[204:207], v[196:199], v[4:7]
	v_mfma_f32_16x16x32_bf16 v[0:3], v[216:219], v[196:199], v[0:3]
	s_setprio 0
	s_add_i32 s75, s75, 2
	s_add_u32 s38, s38, 0x100
	s_addc_u32 s39, s39, 0
	s_add_u32 s73, s73, 0x100
	s_addc_u32 s74, s74, 0
	s_cmp_gt_u32 s75, 13
	s_barrier
	s_cbranch_scc0 .LBB0_150
	v_lshl_add_u32 v151, s36, 8, v144
	s_cmp_gt_i32 s71, 11
	s_mov_b64 s[36:37], -1
	s_cbranch_scc0 .LBB0_155
	s_and_saveexec_b64 s[36:37], s[2:3]
	s_cbranch_execz .LBB0_154
	v_lshl_or_b32 v152, v151, 8, v147
	v_readlane_b32 s38, v253, 59
	v_readlane_b32 s39, v253, 60
	v_or_b32_e32 v153, 0x1000, v152
	s_nop 3
	global_store_dwordx4 v153, v[116:119], s[38:39] nt
	v_or_b32_e32 v153, 0x2000, v152
	global_store_dwordx4 v153, v[108:111], s[38:39] nt
	v_or_b32_e32 v153, 0x3000, v152
	global_store_dwordx4 v153, v[100:103], s[38:39] nt
	v_add_u32_e32 v153, 0x8000, v152
	global_store_dwordx4 v153, v[92:95], s[38:39] nt
	v_add_u32_e32 v153, 0x9000, v152
	global_store_dwordx4 v153, v[84:87], s[38:39] nt
	v_add_u32_e32 v153, 0xa000, v152
	global_store_dwordx4 v153, v[68:71], s[38:39] nt
	v_add_u32_e32 v153, 0xb000, v152
	global_store_dwordx4 v153, v[52:55], s[38:39] nt
	v_or_b32_e32 v153, 16, v152
	global_store_dwordx4 v153, v[120:123], s[38:39] nt
	v_or_b32_e32 v153, 0x1010, v152
	global_store_dwordx4 v153, v[112:115], s[38:39] nt
	v_or_b32_e32 v153, 0x2010, v152
	global_store_dwordx4 v153, v[104:107], s[38:39] nt
	v_or_b32_e32 v153, 0x3010, v152
	global_store_dwordx4 v153, v[96:99], s[38:39] nt
	v_add_u32_e32 v153, 0x8010, v152
	global_store_dwordx4 v153, v[88:91], s[38:39] nt
	v_add_u32_e32 v153, 0x9010, v152
	global_store_dwordx4 v152, v[124:127], s[38:39] nt
	global_store_dwordx4 v153, v[80:83], s[38:39] nt
	v_add_u32_e32 v153, 0xa010, v152
	v_add_u32_e32 v152, 0xb010, v152
	global_store_dwordx4 v153, v[64:67], s[38:39] nt
	global_store_dwordx4 v152, v[48:51], s[38:39] nt

.LBB0_155:
	s_andn2_b64 vcc, exec, s[36:37]
	s_cbranch_vccnz .LBB0_146
	s_lshl_b32 s9, s71, 24
	v_lshl_or_b32 v151, v151, 6, s66
	s_or_b32 s9, s9, s67
	v_add_lshl_u32 v151, v151, s9, 1
	v_or_b32_e32 v152, v151, v145
	v_cvt_pk_bf16_f32 v124, v124, v125
	v_cvt_pk_bf16_f32 v125, v126, v127
	v_cvt_pk_bf16_f32 v126, v120, v121
	v_cvt_pk_bf16_f32 v127, v122, v123
	global_store_dwordx4 v152, v[124:127], s[92:93] nt
	v_cvt_pk_bf16_f32 v116, v116, v117
	v_cvt_pk_bf16_f32 v117, v118, v119
	v_cvt_pk_bf16_f32 v118, v112, v113
	v_add_u32_e32 v112, 0x800, v152
	v_cvt_pk_bf16_f32 v119, v114, v115
	global_store_dwordx4 v112, v[116:119], s[92:93] nt
	v_cvt_pk_bf16_f32 v108, v108, v109
	v_cvt_pk_bf16_f32 v109, v110, v111
	v_cvt_pk_bf16_f32 v110, v104, v105
	v_add_u32_e32 v104, 0x1000, v152
	v_cvt_pk_bf16_f32 v111, v106, v107
	global_store_dwordx4 v104, v[108:111], s[92:93] nt
	v_cvt_pk_bf16_f32 v100, v100, v101
	v_cvt_pk_bf16_f32 v101, v102, v103
	v_cvt_pk_bf16_f32 v102, v96, v97
	v_add_u32_e32 v96, 0x1800, v152
	v_cvt_pk_bf16_f32 v103, v98, v99
	global_store_dwordx4 v96, v[100:103], s[92:93] nt
	v_add_u32_e32 v96, 0x4000, v152
	v_cvt_pk_bf16_f32 v92, v92, v93
	v_cvt_pk_bf16_f32 v93, v94, v95
	v_cvt_pk_bf16_f32 v94, v88, v89
	v_cvt_pk_bf16_f32 v95, v90, v91
	global_store_dwordx4 v96, v[92:95], s[92:93] nt
	v_cvt_pk_bf16_f32 v84, v84, v85
	v_cvt_pk_bf16_f32 v85, v86, v87
	v_cvt_pk_bf16_f32 v86, v80, v81
	v_add_u32_e32 v80, 0x4800, v152
	v_cvt_pk_bf16_f32 v87, v82, v83
	global_store_dwordx4 v80, v[84:87], s[92:93] nt
	v_cvt_pk_bf16_f32 v68, v68, v69
	v_cvt_pk_bf16_f32 v69, v70, v71
	v_cvt_pk_bf16_f32 v70, v64, v65
	v_add_u32_e32 v64, 0x5000, v152
	v_cvt_pk_bf16_f32 v71, v66, v67
	global_store_dwordx4 v64, v[68:71], s[92:93] nt
	v_cvt_pk_bf16_f32 v52, v52, v53
	v_cvt_pk_bf16_f32 v53, v54, v55
	v_cvt_pk_bf16_f32 v54, v48, v49
	v_add_u32_e32 v48, 0x5800, v152
	v_cvt_pk_bf16_f32 v55, v50, v51
	global_store_dwordx4 v48, v[52:55], s[92:93] nt
	v_cvt_pk_bf16_f32 v48, v76, v77
	v_cvt_pk_bf16_f32 v49, v78, v79
	v_cvt_pk_bf16_f32 v50, v72, v73
	v_cvt_pk_bf16_f32 v51, v74, v75
	s_nop 1
	v_add_u32_e32 v52, v151, v145
	v_add_u32_e32 v53, 0x1000000, v52
	global_store_dwordx4 v53, v[48:51], s[92:93] nt
	v_add_u32_e32 v53, 0x1000800, v52
	s_nop 0
	v_cvt_pk_bf16_f32 v48, v60, v61
	v_cvt_pk_bf16_f32 v49, v62, v63
	v_cvt_pk_bf16_f32 v50, v56, v57
	v_cvt_pk_bf16_f32 v51, v58, v59
	global_store_dwordx4 v53, v[48:51], s[92:93] nt
	v_cvt_pk_bf16_f32 v44, v44, v45
	v_cvt_pk_bf16_f32 v45, v46, v47
	v_cvt_pk_bf16_f32 v46, v40, v41
	v_add_u32_e32 v40, 0x1001000, v52
	v_cvt_pk_bf16_f32 v47, v42, v43
	global_store_dwordx4 v40, v[44:47], s[92:93] nt
	v_cvt_pk_bf16_f32 v36, v36, v37
	v_cvt_pk_bf16_f32 v37, v38, v39
	v_cvt_pk_bf16_f32 v38, v32, v33
	v_add_u32_e32 v32, 0x1001800, v52
	v_cvt_pk_bf16_f32 v39, v34, v35
	global_store_dwordx4 v32, v[36:39], s[92:93] nt
	v_add_u32_e32 v32, 0x1004000, v52
	v_cvt_pk_bf16_f32 v28, v28, v29
	v_cvt_pk_bf16_f32 v29, v30, v31
	v_cvt_pk_bf16_f32 v30, v24, v25
	v_cvt_pk_bf16_f32 v31, v26, v27
	global_store_dwordx4 v32, v[28:31], s[92:93] nt
	v_cvt_pk_bf16_f32 v20, v20, v21
	v_cvt_pk_bf16_f32 v21, v22, v23
	v_cvt_pk_bf16_f32 v22, v16, v17
	v_add_u32_e32 v16, 0x1004800, v52
	v_cvt_pk_bf16_f32 v23, v18, v19
	global_store_dwordx4 v16, v[20:23], s[92:93] nt
	v_cvt_pk_bf16_f32 v12, v12, v13
	v_cvt_pk_bf16_f32 v13, v14, v15
	v_cvt_pk_bf16_f32 v14, v8, v9
	v_add_u32_e32 v8, 0x1005000, v52
	v_cvt_pk_bf16_f32 v15, v10, v11
	global_store_dwordx4 v8, v[12:15], s[92:93] nt
	v_cvt_pk_bf16_f32 v4, v4, v5
	v_cvt_pk_bf16_f32 v5, v6, v7
	v_cvt_pk_bf16_f32 v6, v0, v1
	v_add_u32_e32 v0, 0x1005800, v52
	v_cvt_pk_bf16_f32 v7, v2, v3
	global_store_dwordx4 v0, v[4:7], s[92:93] nt
	s_branch .LBB0_146

.LBB0_177:
	ds_read_b128 v[152:155], v149
	ds_read_b128 v[156:159], v149 offset:1024
	ds_read_b128 v[160:163], v149 offset:2048
	ds_read_b128 v[164:167], v149 offset:3072
	s_add_u32 s36, s34, 0xfffc0080
	s_addc_u32 s37, s35, -1
	s_cmp_eq_u32 s68, 12
	s_cselect_b32 s39, s9, s37
	s_cselect_b32 s38, s64, s36
	s_cselect_b32 s37, s3, s67
	s_cselect_b32 s36, s65, s66
	v_lshl_add_u64 v[144:145], s[34:35], 0, v[136:137]
	s_add_i32 m0, s13, 0xc000
	ds_read_b128 v[168:171], v150
	ds_read_b128 v[172:175], v150 offset:1024
	ds_read_b128 v[176:179], v150 offset:2048
	ds_read_b128 v[180:183], v150 offset:3072
	ds_read_b128 v[184:187], v150 offset:4096
	ds_read_b128 v[188:191], v150 offset:5120
	ds_read_b128 v[192:195], v150 offset:6144
	ds_read_b128 v[196:199], v150 offset:7168
	global_load_lds_dwordx4 v[144:145], off
	v_lshl_add_u64 v[144:145], s[34:35], 0, v[138:139]
	s_add_i32 m0, s13, 0xe000
	s_nop 0
	global_load_lds_dwordx4 v[144:145], off
	s_waitcnt lgkmcnt(8)
	s_barrier
	s_waitcnt lgkmcnt(0)
	s_setprio 1
	s_waitcnt lgkmcnt(0)
	v_mfma_f32_16x16x32_bf16 v[124:127], v[152:155], v[168:171], v[124:127]
	v_mfma_f32_16x16x32_bf16 v[120:123], v[160:163], v[168:171], v[120:123]
	v_mfma_f32_16x16x32_bf16 v[112:115], v[152:155], v[176:179], v[112:115]
	v_mfma_f32_16x16x32_bf16 v[104:107], v[160:163], v[176:179], v[104:107]
	v_mfma_f32_16x16x32_bf16 v[96:99], v[152:155], v[184:187], v[96:99]
	v_mfma_f32_16x16x32_bf16 v[88:91], v[160:163], v[184:187], v[88:91]
	v_mfma_f32_16x16x32_bf16 v[80:83], v[152:155], v[192:195], v[80:83]
	v_mfma_f32_16x16x32_bf16 v[72:75], v[160:163], v[192:195], v[72:75]
	v_mfma_f32_16x16x32_bf16 v[124:127], v[156:159], v[172:175], v[124:127]
	v_mfma_f32_16x16x32_bf16 v[120:123], v[164:167], v[172:175], v[120:123]
	v_mfma_f32_16x16x32_bf16 v[112:115], v[156:159], v[180:183], v[112:115]
	v_mfma_f32_16x16x32_bf16 v[104:107], v[164:167], v[180:183], v[104:107]
	v_mfma_f32_16x16x32_bf16 v[96:99], v[156:159], v[188:191], v[96:99]
	v_mfma_f32_16x16x32_bf16 v[88:91], v[164:167], v[188:191], v[88:91]
	v_mfma_f32_16x16x32_bf16 v[80:83], v[156:159], v[196:199], v[80:83]
	v_mfma_f32_16x16x32_bf16 v[72:75], v[164:167], v[196:199], v[72:75]
	s_setprio 0
	s_barrier
	s_add_i32 s69, s55, s42
	v_lshl_add_u64 v[144:145], s[36:37], 0, v[130:131]
	s_mov_b32 m0, s69
	ds_read_b128 v[200:203], v151
	ds_read_b128 v[204:207], v151 offset:1024
	ds_read_b128 v[212:215], v151 offset:2048
	ds_read_b128 v[216:219], v151 offset:3072
	global_load_lds_dwordx4 v[144:145], off
	v_lshl_add_u64 v[208:209], s[36:37], 0, v[134:135]
	s_add_i32 m0, s69, 0x2000
	s_nop 0
	global_load_lds_dwordx4 v[208:209], off
	s_barrier
	s_waitcnt lgkmcnt(0)
	s_setprio 1
	s_waitcnt lgkmcnt(0)
	v_mfma_f32_16x16x32_bf16 v[116:119], v[200:203], v[168:171], v[116:119]
	v_mfma_f32_16x16x32_bf16 v[108:111], v[212:215], v[168:171], v[108:111]
	v_mfma_f32_16x16x32_bf16 v[100:103], v[200:203], v[176:179], v[100:103]
	v_mfma_f32_16x16x32_bf16 v[92:95], v[212:215], v[176:179], v[92:95]
	v_mfma_f32_16x16x32_bf16 v[84:87], v[200:203], v[184:187], v[84:87]
	v_mfma_f32_16x16x32_bf16 v[76:79], v[212:215], v[184:187], v[76:79]
	v_mfma_f32_16x16x32_bf16 v[68:71], v[200:203], v[192:195], v[68:71]
	v_mfma_f32_16x16x32_bf16 v[64:67], v[212:215], v[192:195], v[64:67]
	v_mfma_f32_16x16x32_bf16 v[116:119], v[204:207], v[172:175], v[116:119]
	v_mfma_f32_16x16x32_bf16 v[108:111], v[216:219], v[172:175], v[108:111]
	v_mfma_f32_16x16x32_bf16 v[100:103], v[204:207], v[180:183], v[100:103]
	v_mfma_f32_16x16x32_bf16 v[92:95], v[216:219], v[180:183], v[92:95]
	v_mfma_f32_16x16x32_bf16 v[84:87], v[204:207], v[188:191], v[84:87]
	v_mfma_f32_16x16x32_bf16 v[76:79], v[216:219], v[188:191], v[76:79]
	v_mfma_f32_16x16x32_bf16 v[68:71], v[204:207], v[196:199], v[68:71]
	v_mfma_f32_16x16x32_bf16 v[64:67], v[216:219], v[196:199], v[64:67]
	s_setprio 0
	s_mov_b32 m0, s13
	v_lshl_add_u64 v[220:221], s[38:39], 0, v[128:129]
	s_barrier
	ds_read_b128 v[168:171], v150 offset:16384
	ds_read_b128 v[172:175], v150 offset:17408
	ds_read_b128 v[176:179], v150 offset:18432
	ds_read_b128 v[180:183], v150 offset:19456
	ds_read_b128 v[184:187], v150 offset:20480
	ds_read_b128 v[188:191], v150 offset:21504
	ds_read_b128 v[192:195], v150 offset:22528
	ds_read_b128 v[196:199], v150 offset:23552
	global_load_lds_dwordx4 v[220:221], off
	v_lshl_add_u64 v[222:223], s[38:39], 0, v[132:133]
	s_mov_b32 m0, s43
	s_nop 0
	global_load_lds_dwordx4 v[222:223], off
	s_barrier
	s_waitcnt lgkmcnt(0)
	s_setprio 1
	s_waitcnt lgkmcnt(0)
	v_mfma_f32_16x16x32_bf16 v[60:63], v[152:155], v[168:171], v[60:63]
	v_mfma_f32_16x16x32_bf16 v[56:59], v[160:163], v[168:171], v[56:59]
	v_mfma_f32_16x16x32_bf16 v[52:55], v[152:155], v[176:179], v[52:55]
	v_mfma_f32_16x16x32_bf16 v[44:47], v[160:163], v[176:179], v[44:47]
	v_mfma_f32_16x16x32_bf16 v[36:39], v[152:155], v[184:187], v[36:39]
	v_mfma_f32_16x16x32_bf16 v[28:31], v[160:163], v[184:187], v[28:31]
	v_mfma_f32_16x16x32_bf16 v[20:23], v[152:155], v[192:195], v[20:23]
	v_mfma_f32_16x16x32_bf16 v[12:15], v[160:163], v[192:195], v[12:15]
	v_mfma_f32_16x16x32_bf16 v[60:63], v[156:159], v[172:175], v[60:63]
	v_mfma_f32_16x16x32_bf16 v[56:59], v[164:167], v[172:175], v[56:59]
	v_mfma_f32_16x16x32_bf16 v[52:55], v[156:159], v[180:183], v[52:55]
	v_mfma_f32_16x16x32_bf16 v[44:47], v[164:167], v[180:183], v[44:47]
	v_mfma_f32_16x16x32_bf16 v[36:39], v[156:159], v[188:191], v[36:39]
	v_mfma_f32_16x16x32_bf16 v[28:31], v[164:167], v[188:191], v[28:31]
	v_mfma_f32_16x16x32_bf16 v[20:23], v[156:159], v[196:199], v[20:23]
	v_mfma_f32_16x16x32_bf16 v[12:15], v[164:167], v[196:199], v[12:15]
	s_setprio 0
	s_barrier
	s_add_u32 s70, s36, 0x40000
	s_addc_u32 s71, s37, 0
	s_add_i32 s69, s62, s42
	v_lshl_add_u64 v[152:153], s[70:71], 0, v[130:131]
	s_mov_b32 m0, s69
	s_nop 0
	global_load_lds_dwordx4 v[152:153], off
	v_lshl_add_u64 v[152:153], s[70:71], 0, v[134:135]
	s_add_i32 m0, s69, 0x2000
	s_nop 0
	global_load_lds_dwordx4 v[152:153], off
	s_waitcnt vmcnt(6)
	s_barrier
	s_setprio 1
	v_mfma_f32_16x16x32_bf16 v[48:51], v[200:203], v[168:171], v[48:51]
	v_mfma_f32_16x16x32_bf16 v[40:43], v[212:215], v[168:171], v[40:43]
	v_mfma_f32_16x16x32_bf16 v[32:35], v[200:203], v[176:179], v[32:35]
	v_mfma_f32_16x16x32_bf16 v[24:27], v[212:215], v[176:179], v[24:27]
	v_mfma_f32_16x16x32_bf16 v[16:19], v[200:203], v[184:187], v[16:19]
	v_mfma_f32_16x16x32_bf16 v[8:11], v[212:215], v[184:187], v[8:11]
	v_mfma_f32_16x16x32_bf16 v[4:7], v[200:203], v[192:195], v[4:7]
	v_mfma_f32_16x16x32_bf16 v[0:3], v[212:215], v[192:195], v[0:3]
	v_mfma_f32_16x16x32_bf16 v[48:51], v[204:207], v[172:175], v[48:51]
	v_mfma_f32_16x16x32_bf16 v[40:43], v[216:219], v[172:175], v[40:43]
	v_mfma_f32_16x16x32_bf16 v[32:35], v[204:207], v[180:183], v[32:35]
	v_mfma_f32_16x16x32_bf16 v[24:27], v[216:219], v[180:183], v[24:27]
	v_mfma_f32_16x16x32_bf16 v[16:19], v[204:207], v[188:191], v[16:19]
	v_mfma_f32_16x16x32_bf16 v[8:11], v[216:219], v[188:191], v[8:11]
	v_mfma_f32_16x16x32_bf16 v[4:7], v[204:207], v[196:199], v[4:7]
	v_mfma_f32_16x16x32_bf16 v[0:3], v[216:219], v[196:199], v[0:3]
	s_setprio 0
	s_add_i32 s69, 0, 0x18000
	v_add_u32_e32 v164, s69, v147
	s_barrier
	ds_read_b128 v[152:155], v164
	ds_read_b128 v[156:159], v164 offset:1024
	ds_read_b128 v[160:163], v164 offset:2048
	ds_read_b128 v[164:167], v164 offset:3072
	s_add_u32 s38, s38, 0x40000
	s_addc_u32 s39, s39, 0
	s_mov_b32 m0, s48
	v_lshl_add_u64 v[200:201], s[38:39], 0, v[128:129]
	ds_read_b128 v[168:171], v150 offset:32768
	ds_read_b128 v[172:175], v150 offset:33792
	ds_read_b128 v[176:179], v150 offset:34816
	ds_read_b128 v[180:183], v150 offset:35840
	ds_read_b128 v[184:187], v150 offset:36864
	ds_read_b128 v[188:191], v150 offset:37888
	ds_read_b128 v[192:195], v150 offset:38912
	ds_read_b128 v[196:199], v150 offset:39936
	global_load_lds_dwordx4 v[200:201], off
	v_lshl_add_u64 v[200:201], s[38:39], 0, v[132:133]
	s_mov_b32 m0, s49
	s_nop 0
	global_load_lds_dwordx4 v[200:201], off
	s_waitcnt lgkmcnt(8)
	s_barrier
	s_waitcnt lgkmcnt(0)
	s_setprio 1
	s_waitcnt lgkmcnt(0)
	v_mfma_f32_16x16x32_bf16 v[124:127], v[152:155], v[168:171], v[124:127]
	v_mfma_f32_16x16x32_bf16 v[120:123], v[160:163], v[168:171], v[120:123]
	v_mfma_f32_16x16x32_bf16 v[112:115], v[152:155], v[176:179], v[112:115]
	v_mfma_f32_16x16x32_bf16 v[104:107], v[160:163], v[176:179], v[104:107]
	v_mfma_f32_16x16x32_bf16 v[96:99], v[152:155], v[184:187], v[96:99]
	v_mfma_f32_16x16x32_bf16 v[88:91], v[160:163], v[184:187], v[88:91]
	v_mfma_f32_16x16x32_bf16 v[80:83], v[152:155], v[192:195], v[80:83]
	v_mfma_f32_16x16x32_bf16 v[72:75], v[160:163], v[192:195], v[72:75]
	v_mfma_f32_16x16x32_bf16 v[124:127], v[156:159], v[172:175], v[124:127]
	v_mfma_f32_16x16x32_bf16 v[120:123], v[164:167], v[172:175], v[120:123]
	v_mfma_f32_16x16x32_bf16 v[112:115], v[156:159], v[180:183], v[112:115]
	v_mfma_f32_16x16x32_bf16 v[104:107], v[164:167], v[180:183], v[104:107]
	v_mfma_f32_16x16x32_bf16 v[96:99], v[156:159], v[188:191], v[96:99]
	v_mfma_f32_16x16x32_bf16 v[88:91], v[164:167], v[188:191], v[88:91]
	v_mfma_f32_16x16x32_bf16 v[80:83], v[156:159], v[196:199], v[80:83]
	v_mfma_f32_16x16x32_bf16 v[72:75], v[164:167], v[196:199], v[72:75]
	s_setprio 0
	s_barrier
	s_add_i32 s38, 0, 0x1c000
	s_add_i32 s39, s69, s42
	v_add_u32_e32 v211, s38, v147
	v_lshl_add_u64 v[144:145], v[144:145], 0, s[0:1]
	s_mov_b32 m0, s39
	ds_read_b128 v[200:203], v211
	ds_read_b128 v[204:207], v211 offset:1024
	ds_read_b128 v[212:215], v211 offset:2048
	ds_read_b128 v[216:219], v211 offset:3072
	global_load_lds_dwordx4 v[144:145], off
	v_lshl_add_u64 v[144:145], v[208:209], 0, s[0:1]
	s_add_i32 m0, s39, 0x2000
	s_nop 0
	global_load_lds_dwordx4 v[144:145], off
	s_barrier
	s_waitcnt lgkmcnt(0)
	s_setprio 1
	s_waitcnt lgkmcnt(0)
	v_mfma_f32_16x16x32_bf16 v[116:119], v[200:203], v[168:171], v[116:119]
	v_mfma_f32_16x16x32_bf16 v[108:111], v[212:215], v[168:171], v[108:111]
	v_mfma_f32_16x16x32_bf16 v[100:103], v[200:203], v[176:179], v[100:103]
	v_mfma_f32_16x16x32_bf16 v[92:95], v[212:215], v[176:179], v[92:95]
	v_mfma_f32_16x16x32_bf16 v[84:87], v[200:203], v[184:187], v[84:87]
	v_mfma_f32_16x16x32_bf16 v[76:79], v[212:215], v[184:187], v[76:79]
	v_mfma_f32_16x16x32_bf16 v[68:71], v[200:203], v[192:195], v[68:71]
	v_mfma_f32_16x16x32_bf16 v[64:67], v[212:215], v[192:195], v[64:67]
	v_mfma_f32_16x16x32_bf16 v[116:119], v[204:207], v[172:175], v[116:119]
	v_mfma_f32_16x16x32_bf16 v[108:111], v[216:219], v[172:175], v[108:111]
	v_mfma_f32_16x16x32_bf16 v[100:103], v[204:207], v[180:183], v[100:103]
	v_mfma_f32_16x16x32_bf16 v[92:95], v[216:219], v[180:183], v[92:95]
	v_mfma_f32_16x16x32_bf16 v[84:87], v[204:207], v[188:191], v[84:87]
	v_mfma_f32_16x16x32_bf16 v[76:79], v[216:219], v[188:191], v[76:79]
	v_mfma_f32_16x16x32_bf16 v[68:71], v[204:207], v[196:199], v[68:71]
	v_mfma_f32_16x16x32_bf16 v[64:67], v[216:219], v[196:199], v[64:67]
	s_setprio 0
	s_mov_b32 m0, s51
	v_lshl_add_u64 v[144:145], v[220:221], 0, s[0:1]
	s_barrier
	ds_read_b128 v[168:171], v150 offset:49152
	ds_read_b128 v[172:175], v150 offset:50176
	ds_read_b128 v[176:179], v150 offset:51200
	ds_read_b128 v[180:183], v150 offset:52224
	ds_read_b128 v[184:187], v150 offset:53248
	ds_read_b128 v[188:191], v150 offset:54272
	ds_read_b128 v[192:195], v150 offset:55296
	ds_read_b128 v[196:199], v150 offset:56320
	global_load_lds_dwordx4 v[144:145], off
	v_lshl_add_u64 v[144:145], v[222:223], 0, s[0:1]
	s_mov_b32 m0, s54
	s_nop 0
	global_load_lds_dwordx4 v[144:145], off
	s_barrier
	s_waitcnt lgkmcnt(0)
	s_setprio 1
	s_waitcnt lgkmcnt(0)
	v_mfma_f32_16x16x32_bf16 v[60:63], v[152:155], v[168:171], v[60:63]
	v_mfma_f32_16x16x32_bf16 v[56:59], v[160:163], v[168:171], v[56:59]
	v_mfma_f32_16x16x32_bf16 v[52:55], v[152:155], v[176:179], v[52:55]
	v_mfma_f32_16x16x32_bf16 v[44:47], v[160:163], v[176:179], v[44:47]
	v_mfma_f32_16x16x32_bf16 v[36:39], v[152:155], v[184:187], v[36:39]
	v_mfma_f32_16x16x32_bf16 v[28:31], v[160:163], v[184:187], v[28:31]
	v_mfma_f32_16x16x32_bf16 v[20:23], v[152:155], v[192:195], v[20:23]
	v_mfma_f32_16x16x32_bf16 v[12:15], v[160:163], v[192:195], v[12:15]
	v_mfma_f32_16x16x32_bf16 v[60:63], v[156:159], v[172:175], v[60:63]
	v_mfma_f32_16x16x32_bf16 v[56:59], v[164:167], v[172:175], v[56:59]
	v_mfma_f32_16x16x32_bf16 v[52:55], v[156:159], v[180:183], v[52:55]
	v_mfma_f32_16x16x32_bf16 v[44:47], v[164:167], v[180:183], v[44:47]
	v_mfma_f32_16x16x32_bf16 v[36:39], v[156:159], v[188:191], v[36:39]
	v_mfma_f32_16x16x32_bf16 v[28:31], v[164:167], v[188:191], v[28:31]
	v_mfma_f32_16x16x32_bf16 v[20:23], v[156:159], v[196:199], v[20:23]
	v_mfma_f32_16x16x32_bf16 v[12:15], v[164:167], v[196:199], v[12:15]
	s_setprio 0
	s_barrier
	s_add_u32 s36, s36, 0x40080
	s_addc_u32 s37, s37, 0
	s_add_i32 s38, s38, s42
	v_lshl_add_u64 v[144:145], s[36:37], 0, v[130:131]
	s_mov_b32 m0, s38
	s_nop 0
	global_load_lds_dwordx4 v[144:145], off
	v_lshl_add_u64 v[144:145], s[36:37], 0, v[134:135]
	s_add_i32 m0, s38, 0x2000
	s_nop 0
	global_load_lds_dwordx4 v[144:145], off
	s_waitcnt vmcnt(6)
	s_barrier
	s_setprio 1
	v_mfma_f32_16x16x32_bf16 v[48:51], v[200:203], v[168:171], v[48:51]
	v_mfma_f32_16x16x32_bf16 v[40:43], v[212:215], v[168:171], v[40:43]
	v_mfma_f32_16x16x32_bf16 v[32:35], v[200:203], v[176:179], v[32:35]
	v_mfma_f32_16x16x32_bf16 v[24:27], v[212:215], v[176:179], v[24:27]
	v_mfma_f32_16x16x32_bf16 v[16:19], v[200:203], v[184:187], v[16:19]
	v_mfma_f32_16x16x32_bf16 v[8:11], v[212:215], v[184:187], v[8:11]
	v_mfma_f32_16x16x32_bf16 v[4:7], v[200:203], v[192:195], v[4:7]
	v_mfma_f32_16x16x32_bf16 v[0:3], v[212:215], v[192:195], v[0:3]
	v_mfma_f32_16x16x32_bf16 v[48:51], v[204:207], v[172:175], v[48:51]
	v_mfma_f32_16x16x32_bf16 v[40:43], v[216:219], v[172:175], v[40:43]
	v_mfma_f32_16x16x32_bf16 v[32:35], v[204:207], v[180:183], v[32:35]
	v_mfma_f32_16x16x32_bf16 v[24:27], v[216:219], v[180:183], v[24:27]
	v_mfma_f32_16x16x32_bf16 v[16:19], v[204:207], v[188:191], v[16:19]
	v_mfma_f32_16x16x32_bf16 v[8:11], v[216:219], v[188:191], v[8:11]
	v_mfma_f32_16x16x32_bf16 v[4:7], v[204:207], v[196:199], v[4:7]
	v_mfma_f32_16x16x32_bf16 v[0:3], v[216:219], v[196:199], v[0:3]
	s_setprio 0
	s_add_i32 s68, s68, 2
	s_add_u32 s34, s34, 0x100
	s_addc_u32 s35, s35, 0
	s_add_u32 s66, s66, 0x100
	s_addc_u32 s67, s67, 0
	s_cmp_gt_u32 s68, 13
	s_barrier
	s_cbranch_scc0 .LBB0_177
	v_lshl_add_u32 v152, s12, 8, v146
	v_ashrrev_i32_e32 v153, 31, v152
	v_lshl_or_b32 v144, s63, 8, v148
	v_readlane_b32 s34, v253, 61
	v_ashrrev_i32_e32 v145, 31, v144
	v_lshlrev_b64 v[154:155], 17, v[152:153]
	v_readlane_b32 s35, v253, 62
	v_lshlrev_b64 v[156:157], 1, v[144:145]
	v_cvt_pk_bf16_f32 v124, v124, v125
	v_cvt_pk_bf16_f32 v125, v126, v127
	v_cvt_pk_bf16_f32 v126, v120, v121
	s_nop 0
	v_lshl_add_u64 v[154:155], s[34:35], 0, v[154:155]
	v_lshl_add_u64 v[144:145], v[154:155], 0, v[156:157]
	v_cvt_pk_bf16_f32 v127, v122, v123
	global_store_dwordx4 v[144:145], v[124:127], off nt
	v_cvt_pk_bf16_f32 v116, v116, v117
	v_cvt_pk_bf16_f32 v117, v118, v119
	v_cvt_pk_bf16_f32 v118, v108, v109
	v_or_b32_e32 v108, 16, v152
	v_ashrrev_i32_e32 v109, 31, v108
	v_lshlrev_b64 v[108:109], 17, v[108:109]
	v_lshl_add_u64 v[108:109], s[34:35], 0, v[108:109]
	v_cvt_pk_bf16_f32 v119, v110, v111
	global_store_dwordx4 v[144:145], v[116:119], off offset:256 nt
	s_mov_b32 s3, 0x1000000
	s_mov_b32 s63, s2
	v_lshl_add_u64 v[116:117], v[108:109], 0, v[156:157]
	v_cvt_pk_bf16_f32 v108, v112, v113
	v_cvt_pk_bf16_f32 v109, v114, v115
	v_cvt_pk_bf16_f32 v110, v104, v105
	v_cvt_pk_bf16_f32 v111, v106, v107
	global_store_dwordx4 v[116:117], v[108:111], off nt
	v_cvt_pk_bf16_f32 v100, v100, v101
	v_cvt_pk_bf16_f32 v101, v102, v103
	v_cvt_pk_bf16_f32 v102, v92, v93
	v_or_b32_e32 v92, 32, v152
	v_ashrrev_i32_e32 v93, 31, v92
	v_lshlrev_b64 v[92:93], 17, v[92:93]
	v_lshl_add_u64 v[92:93], s[34:35], 0, v[92:93]
	v_cvt_pk_bf16_f32 v103, v94, v95
	global_store_dwordx4 v[116:117], v[100:103], off offset:256 nt
	s_mov_b32 s12, s8
	s_mov_b64 s[36:37], s[30:31]
	v_lshl_add_u64 v[100:101], v[92:93], 0, v[156:157]
	v_cvt_pk_bf16_f32 v92, v96, v97
	v_cvt_pk_bf16_f32 v93, v98, v99
	v_cvt_pk_bf16_f32 v94, v88, v89
	v_cvt_pk_bf16_f32 v95, v90, v91
	global_store_dwordx4 v[100:101], v[92:95], off nt
	v_cvt_pk_bf16_f32 v84, v84, v85
	v_cvt_pk_bf16_f32 v85, v86, v87
	v_cvt_pk_bf16_f32 v86, v76, v77
	v_or_b32_e32 v76, 48, v152
	v_ashrrev_i32_e32 v77, 31, v76
	v_lshlrev_b64 v[76:77], 17, v[76:77]
	v_lshl_add_u64 v[76:77], s[34:35], 0, v[76:77]
	v_cvt_pk_bf16_f32 v87, v78, v79
	global_store_dwordx4 v[100:101], v[84:87], off offset:256 nt
	s_mov_b64 s[34:35], 0x1000000
	s_nop 0
	v_lshl_add_u64 v[84:85], v[76:77], 0, v[156:157]
	v_cvt_pk_bf16_f32 v76, v80, v81
	v_cvt_pk_bf16_f32 v77, v82, v83
	v_cvt_pk_bf16_f32 v78, v72, v73
	v_cvt_pk_bf16_f32 v79, v74, v75
	global_store_dwordx4 v[84:85], v[76:79], off nt
	v_cvt_pk_bf16_f32 v68, v68, v69
	v_cvt_pk_bf16_f32 v69, v70, v71
	v_cvt_pk_bf16_f32 v70, v64, v65
	v_cvt_pk_bf16_f32 v71, v66, v67
	global_store_dwordx4 v[84:85], v[68:71], off offset:256 nt
	v_cvt_pk_bf16_f32 v60, v60, v61
	v_cvt_pk_bf16_f32 v61, v62, v63
	v_cvt_pk_bf16_f32 v62, v56, v57
	v_add_co_u32_e32 v56, vcc, s3, v144
	v_lshl_add_u64 v[64:65], v[144:145], 0, s[34:35]
	s_nop 0
	v_addc_co_u32_e32 v57, vcc, 0, v145, vcc
	s_mov_b32 s3, 0x1200000
	v_cvt_pk_bf16_f32 v63, v58, v59
	global_store_dwordx4 v[56:57], v[60:63], off nt
	v_cvt_pk_bf16_f32 v48, v48, v49
	v_cvt_pk_bf16_f32 v49, v50, v51
	v_cvt_pk_bf16_f32 v50, v40, v41
	v_cvt_pk_bf16_f32 v51, v42, v43
	global_store_dwordx4 v[64:65], v[48:51], off offset:256 nt
	s_mov_b64 s[34:35], 0x1200000
	v_cvt_pk_bf16_f32 v40, v52, v53
	v_cvt_pk_bf16_f32 v41, v54, v55
	v_cvt_pk_bf16_f32 v42, v44, v45
	v_add_co_u32_e32 v44, vcc, s3, v144
	v_lshl_add_u64 v[48:49], v[144:145], 0, s[34:35]
	s_nop 0
	v_addc_co_u32_e32 v45, vcc, 0, v145, vcc
	s_mov_b32 s3, 0x1400000
	v_cvt_pk_bf16_f32 v43, v46, v47
	global_store_dwordx4 v[44:45], v[40:43], off nt
	v_cvt_pk_bf16_f32 v32, v32, v33
	v_cvt_pk_bf16_f32 v33, v34, v35
	v_cvt_pk_bf16_f32 v34, v24, v25
	v_cvt_pk_bf16_f32 v35, v26, v27
	global_store_dwordx4 v[48:49], v[32:35], off offset:256 nt
	s_mov_b64 s[34:35], 0x1400000
	v_cvt_pk_bf16_f32 v24, v36, v37
	v_cvt_pk_bf16_f32 v25, v38, v39
	v_cvt_pk_bf16_f32 v26, v28, v29
	v_add_co_u32_e32 v28, vcc, s3, v144
	v_lshl_add_u64 v[32:33], v[144:145], 0, s[34:35]
	s_nop 0
	v_addc_co_u32_e32 v29, vcc, 0, v145, vcc
	s_mov_b32 s3, 0x1600000
	v_cvt_pk_bf16_f32 v27, v30, v31
	global_store_dwordx4 v[28:29], v[24:27], off nt
	v_cvt_pk_bf16_f32 v16, v16, v17
	v_cvt_pk_bf16_f32 v17, v18, v19
	v_cvt_pk_bf16_f32 v18, v8, v9
	v_cvt_pk_bf16_f32 v19, v10, v11
	global_store_dwordx4 v[32:33], v[16:19], off offset:256 nt
	v_cvt_pk_bf16_f32 v8, v20, v21
	v_cvt_pk_bf16_f32 v9, v22, v23
	v_cvt_pk_bf16_f32 v10, v12, v13
	v_add_co_u32_e32 v12, vcc, s3, v144
	s_mov_b64 s[34:35], 0x1600000
	s_nop 0
	v_addc_co_u32_e32 v13, vcc, 0, v145, vcc
	v_lshl_add_u64 v[16:17], v[144:145], 0, s[34:35]
	s_and_b64 vcc, exec, s[4:5]
	s_mov_b64 s[34:35], s[14:15]
	v_cvt_pk_bf16_f32 v11, v14, v15
	global_store_dwordx4 v[12:13], v[8:11], off nt
	v_cvt_pk_bf16_f32 v4, v4, v5
	v_cvt_pk_bf16_f32 v5, v6, v7
	v_cvt_pk_bf16_f32 v6, v0, v1
	v_cvt_pk_bf16_f32 v7, v2, v3
	global_store_dwordx4 v[16:17], v[4:7], off offset:256 nt
	s_cbranch_vccz .LBB0_170
	s_waitcnt vmcnt(0)
	s_cmpk_gt_u32 s40, 0xff
	s_cbranch_scc1 .LBB0_181
	s_barrier

.LBB0_200:
	s_add_u32 s48, s42, 0xfffc0080
	s_addc_u32 s49, s43, -1
	s_add_i32 s81, 0, 0x10000
	v_add_u32_e32 v140, s81, v144
	ds_read_b128 v[148:151], v140
	ds_read_b128 v[152:155], v140 offset:1024
	ds_read_b128 v[156:159], v140 offset:2048
	ds_read_b128 v[160:163], v140 offset:3072
	s_cmp_eq_u32 s80, 12
	s_cselect_b32 s51, s35, s49
	s_cselect_b32 s50, s76, s48
	s_cselect_b32 s49, s31, s79
	s_cselect_b32 s48, s77, s78
	v_lshl_add_u64 v[140:141], s[42:43], 0, v[136:137]
	s_add_i32 m0, s37, 0xc000
	ds_read_b128 v[164:167], v146
	ds_read_b128 v[168:171], v146 offset:1024
	ds_read_b128 v[172:175], v146 offset:2048
	ds_read_b128 v[176:179], v146 offset:3072
	ds_read_b128 v[180:183], v146 offset:4096
	ds_read_b128 v[184:187], v146 offset:5120
	ds_read_b128 v[188:191], v146 offset:6144
	ds_read_b128 v[192:195], v146 offset:7168
	global_load_lds_dwordx4 v[140:141], off
	v_lshl_add_u64 v[140:141], s[42:43], 0, v[138:139]
	s_add_i32 m0, s37, 0xe000
	s_nop 0
	global_load_lds_dwordx4 v[140:141], off
	s_waitcnt lgkmcnt(8)
	s_barrier
	s_waitcnt lgkmcnt(0)
	s_setprio 1
	s_waitcnt lgkmcnt(0)
	v_mfma_f32_16x16x32_bf16 v[124:127], v[148:151], v[164:167], v[124:127]
	v_mfma_f32_16x16x32_bf16 v[120:123], v[156:159], v[164:167], v[120:123]
	v_mfma_f32_16x16x32_bf16 v[116:119], v[148:151], v[172:175], v[116:119]
	v_mfma_f32_16x16x32_bf16 v[108:111], v[156:159], v[172:175], v[108:111]
	v_mfma_f32_16x16x32_bf16 v[100:103], v[148:151], v[180:183], v[100:103]
	v_mfma_f32_16x16x32_bf16 v[92:95], v[156:159], v[180:183], v[92:95]
	v_mfma_f32_16x16x32_bf16 v[84:87], v[148:151], v[188:191], v[84:87]
	v_mfma_f32_16x16x32_bf16 v[76:79], v[156:159], v[188:191], v[76:79]
	v_mfma_f32_16x16x32_bf16 v[124:127], v[152:155], v[168:171], v[124:127]
	v_mfma_f32_16x16x32_bf16 v[120:123], v[160:163], v[168:171], v[120:123]
	v_mfma_f32_16x16x32_bf16 v[116:119], v[152:155], v[176:179], v[116:119]
	v_mfma_f32_16x16x32_bf16 v[108:111], v[160:163], v[176:179], v[108:111]
	v_mfma_f32_16x16x32_bf16 v[100:103], v[152:155], v[184:187], v[100:103]
	v_mfma_f32_16x16x32_bf16 v[92:95], v[160:163], v[184:187], v[92:95]
	v_mfma_f32_16x16x32_bf16 v[84:87], v[152:155], v[192:195], v[84:87]
	v_mfma_f32_16x16x32_bf16 v[76:79], v[160:163], v[192:195], v[76:79]
	s_setprio 0
	s_barrier
	s_add_i32 s84, 0, 0x14000
	v_add_u32_e32 v140, s84, v144
	s_add_i32 s81, s81, s69
	ds_read_b128 v[196:199], v140
	ds_read_b128 v[200:203], v140 offset:1024
	ds_read_b128 v[204:207], v140 offset:2048
	ds_read_b128 v[212:215], v140 offset:3072
	v_lshl_add_u64 v[140:141], s[48:49], 0, v[128:129]
	s_mov_b32 m0, s81
	v_lshl_add_u64 v[208:209], s[48:49], 0, v[134:135]
	global_load_lds_dwordx4 v[140:141], off
	s_add_i32 m0, s81, 0x2000
	s_nop 0
	global_load_lds_dwordx4 v[208:209], off
	s_barrier
	s_waitcnt lgkmcnt(0)
	s_setprio 1
	s_waitcnt lgkmcnt(0)
	v_mfma_f32_16x16x32_bf16 v[112:115], v[196:199], v[164:167], v[112:115]
	v_mfma_f32_16x16x32_bf16 v[104:107], v[204:207], v[164:167], v[104:107]
	v_mfma_f32_16x16x32_bf16 v[96:99], v[196:199], v[172:175], v[96:99]
	v_mfma_f32_16x16x32_bf16 v[88:91], v[204:207], v[172:175], v[88:91]
	v_mfma_f32_16x16x32_bf16 v[80:83], v[196:199], v[180:183], v[80:83]
	v_mfma_f32_16x16x32_bf16 v[72:75], v[204:207], v[180:183], v[72:75]
	v_mfma_f32_16x16x32_bf16 v[68:71], v[196:199], v[188:191], v[68:71]
	v_mfma_f32_16x16x32_bf16 v[64:67], v[204:207], v[188:191], v[64:67]
	v_mfma_f32_16x16x32_bf16 v[112:115], v[200:203], v[168:171], v[112:115]
	v_mfma_f32_16x16x32_bf16 v[104:107], v[212:215], v[168:171], v[104:107]
	v_mfma_f32_16x16x32_bf16 v[96:99], v[200:203], v[176:179], v[96:99]
	v_mfma_f32_16x16x32_bf16 v[88:91], v[212:215], v[176:179], v[88:91]
	v_mfma_f32_16x16x32_bf16 v[80:83], v[200:203], v[184:187], v[80:83]
	v_mfma_f32_16x16x32_bf16 v[72:75], v[212:215], v[184:187], v[72:75]
	v_mfma_f32_16x16x32_bf16 v[68:71], v[200:203], v[192:195], v[68:71]
	v_mfma_f32_16x16x32_bf16 v[64:67], v[212:215], v[192:195], v[64:67]
	s_setprio 0
	s_mov_b32 m0, s37
	v_lshl_add_u64 v[216:217], s[50:51], 0, v[130:131]
	s_barrier
	ds_read_b128 v[164:167], v146 offset:16384
	ds_read_b128 v[168:171], v146 offset:17408
	ds_read_b128 v[172:175], v146 offset:18432
	ds_read_b128 v[176:179], v146 offset:19456
	ds_read_b128 v[180:183], v146 offset:20480
	ds_read_b128 v[184:187], v146 offset:21504
	ds_read_b128 v[188:191], v146 offset:22528
	ds_read_b128 v[192:195], v146 offset:23552
	global_load_lds_dwordx4 v[216:217], off
	v_lshl_add_u64 v[218:219], s[50:51], 0, v[132:133]
	s_mov_b32 m0, s70
	s_nop 0
	global_load_lds_dwordx4 v[218:219], off
	s_barrier
	s_waitcnt lgkmcnt(0)
	s_setprio 1
	s_waitcnt lgkmcnt(0)
	v_mfma_f32_16x16x32_bf16 v[60:63], v[148:151], v[164:167], v[60:63]
	v_mfma_f32_16x16x32_bf16 v[56:59], v[156:159], v[164:167], v[56:59]
	v_mfma_f32_16x16x32_bf16 v[52:55], v[148:151], v[172:175], v[52:55]
	v_mfma_f32_16x16x32_bf16 v[44:47], v[156:159], v[172:175], v[44:47]
	v_mfma_f32_16x16x32_bf16 v[36:39], v[148:151], v[180:183], v[36:39]
	v_mfma_f32_16x16x32_bf16 v[28:31], v[156:159], v[180:183], v[28:31]
	v_mfma_f32_16x16x32_bf16 v[20:23], v[148:151], v[188:191], v[20:23]
	v_mfma_f32_16x16x32_bf16 v[12:15], v[156:159], v[188:191], v[12:15]
	v_mfma_f32_16x16x32_bf16 v[60:63], v[152:155], v[168:171], v[60:63]
	v_mfma_f32_16x16x32_bf16 v[56:59], v[160:163], v[168:171], v[56:59]
	v_mfma_f32_16x16x32_bf16 v[52:55], v[152:155], v[176:179], v[52:55]
	v_mfma_f32_16x16x32_bf16 v[44:47], v[160:163], v[176:179], v[44:47]
	v_mfma_f32_16x16x32_bf16 v[36:39], v[152:155], v[184:187], v[36:39]
	v_mfma_f32_16x16x32_bf16 v[28:31], v[160:163], v[184:187], v[28:31]
	v_mfma_f32_16x16x32_bf16 v[20:23], v[152:155], v[192:195], v[20:23]
	v_mfma_f32_16x16x32_bf16 v[12:15], v[160:163], v[192:195], v[12:15]
	s_setprio 0
	s_barrier
	s_add_u32 s82, s48, 0x40000
	s_addc_u32 s83, s49, 0
	s_add_i32 s81, s84, s69
	v_lshl_add_u64 v[148:149], s[82:83], 0, v[128:129]
	s_mov_b32 m0, s81
	s_nop 0
	global_load_lds_dwordx4 v[148:149], off
	v_lshl_add_u64 v[148:149], s[82:83], 0, v[134:135]
	s_add_i32 m0, s81, 0x2000
	s_nop 0
	global_load_lds_dwordx4 v[148:149], off
	s_waitcnt vmcnt(6)
	s_barrier
	s_setprio 1
	v_mfma_f32_16x16x32_bf16 v[48:51], v[196:199], v[164:167], v[48:51]
	v_mfma_f32_16x16x32_bf16 v[40:43], v[204:207], v[164:167], v[40:43]
	v_mfma_f32_16x16x32_bf16 v[32:35], v[196:199], v[172:175], v[32:35]
	v_mfma_f32_16x16x32_bf16 v[24:27], v[204:207], v[172:175], v[24:27]
	v_mfma_f32_16x16x32_bf16 v[16:19], v[196:199], v[180:183], v[16:19]
	v_mfma_f32_16x16x32_bf16 v[8:11], v[204:207], v[180:183], v[8:11]
	v_mfma_f32_16x16x32_bf16 v[4:7], v[196:199], v[188:191], v[4:7]
	v_mfma_f32_16x16x32_bf16 v[0:3], v[204:207], v[188:191], v[0:3]
	v_mfma_f32_16x16x32_bf16 v[48:51], v[200:203], v[168:171], v[48:51]
	v_mfma_f32_16x16x32_bf16 v[40:43], v[212:215], v[168:171], v[40:43]
	v_mfma_f32_16x16x32_bf16 v[32:35], v[200:203], v[176:179], v[32:35]
	v_mfma_f32_16x16x32_bf16 v[24:27], v[212:215], v[176:179], v[24:27]
	v_mfma_f32_16x16x32_bf16 v[16:19], v[200:203], v[184:187], v[16:19]
	v_mfma_f32_16x16x32_bf16 v[8:11], v[212:215], v[184:187], v[8:11]
	v_mfma_f32_16x16x32_bf16 v[4:7], v[200:203], v[192:195], v[4:7]
	v_mfma_f32_16x16x32_bf16 v[0:3], v[212:215], v[192:195], v[0:3]
	s_setprio 0
	s_add_i32 s81, 0, 0x18000
	v_add_u32_e32 v147, s81, v144
	s_barrier
	ds_read_b128 v[148:151], v147
	ds_read_b128 v[152:155], v147 offset:1024
	ds_read_b128 v[156:159], v147 offset:2048
	ds_read_b128 v[160:163], v147 offset:3072
	s_add_u32 s50, s50, 0x40000
	s_addc_u32 s51, s51, 0
	s_mov_b32 m0, s71
	v_lshl_add_u64 v[196:197], s[50:51], 0, v[130:131]
	ds_read_b128 v[164:167], v146 offset:32768
	ds_read_b128 v[168:171], v146 offset:33792
	ds_read_b128 v[172:175], v146 offset:34816
	ds_read_b128 v[176:179], v146 offset:35840
	ds_read_b128 v[180:183], v146 offset:36864
	ds_read_b128 v[184:187], v146 offset:37888
	ds_read_b128 v[188:191], v146 offset:38912
	ds_read_b128 v[192:195], v146 offset:39936
	global_load_lds_dwordx4 v[196:197], off
	v_lshl_add_u64 v[196:197], s[50:51], 0, v[132:133]
	s_mov_b32 m0, s72
	s_nop 0
	global_load_lds_dwordx4 v[196:197], off
	s_waitcnt lgkmcnt(8)
	s_barrier
	s_waitcnt lgkmcnt(0)
	s_setprio 1
	s_waitcnt lgkmcnt(0)
	v_mfma_f32_16x16x32_bf16 v[124:127], v[148:151], v[164:167], v[124:127]
	v_mfma_f32_16x16x32_bf16 v[120:123], v[156:159], v[164:167], v[120:123]
	v_mfma_f32_16x16x32_bf16 v[116:119], v[148:151], v[172:175], v[116:119]
	v_mfma_f32_16x16x32_bf16 v[108:111], v[156:159], v[172:175], v[108:111]
	v_mfma_f32_16x16x32_bf16 v[100:103], v[148:151], v[180:183], v[100:103]
	v_mfma_f32_16x16x32_bf16 v[92:95], v[156:159], v[180:183], v[92:95]
	v_mfma_f32_16x16x32_bf16 v[84:87], v[148:151], v[188:191], v[84:87]
	v_mfma_f32_16x16x32_bf16 v[76:79], v[156:159], v[188:191], v[76:79]
	v_mfma_f32_16x16x32_bf16 v[124:127], v[152:155], v[168:171], v[124:127]
	v_mfma_f32_16x16x32_bf16 v[120:123], v[160:163], v[168:171], v[120:123]
	v_mfma_f32_16x16x32_bf16 v[116:119], v[152:155], v[176:179], v[116:119]
	v_mfma_f32_16x16x32_bf16 v[108:111], v[160:163], v[176:179], v[108:111]
	v_mfma_f32_16x16x32_bf16 v[100:103], v[152:155], v[184:187], v[100:103]
	v_mfma_f32_16x16x32_bf16 v[92:95], v[160:163], v[184:187], v[92:95]
	v_mfma_f32_16x16x32_bf16 v[84:87], v[152:155], v[192:195], v[84:87]
	v_mfma_f32_16x16x32_bf16 v[76:79], v[160:163], v[192:195], v[76:79]
	s_setprio 0
	s_barrier
	s_add_i32 s50, 0, 0x1c000
	s_add_i32 s51, s81, s69
	v_add_u32_e32 v147, s50, v144
	v_lshl_add_u64 v[140:141], v[140:141], 0, s[2:3]
	s_mov_b32 m0, s51
	ds_read_b128 v[196:199], v147
	ds_read_b128 v[200:203], v147 offset:1024
	ds_read_b128 v[204:207], v147 offset:2048
	ds_read_b128 v[212:215], v147 offset:3072
	global_load_lds_dwordx4 v[140:141], off
	v_lshl_add_u64 v[140:141], v[208:209], 0, s[2:3]
	s_add_i32 m0, s51, 0x2000
	s_nop 0
	global_load_lds_dwordx4 v[140:141], off
	s_barrier
	s_waitcnt lgkmcnt(0)
	s_setprio 1
	s_waitcnt lgkmcnt(0)
	v_mfma_f32_16x16x32_bf16 v[112:115], v[196:199], v[164:167], v[112:115]
	v_mfma_f32_16x16x32_bf16 v[104:107], v[204:207], v[164:167], v[104:107]
	v_mfma_f32_16x16x32_bf16 v[96:99], v[196:199], v[172:175], v[96:99]
	v_mfma_f32_16x16x32_bf16 v[88:91], v[204:207], v[172:175], v[88:91]
	v_mfma_f32_16x16x32_bf16 v[80:83], v[196:199], v[180:183], v[80:83]
	v_mfma_f32_16x16x32_bf16 v[72:75], v[204:207], v[180:183], v[72:75]
	v_mfma_f32_16x16x32_bf16 v[68:71], v[196:199], v[188:191], v[68:71]
	v_mfma_f32_16x16x32_bf16 v[64:67], v[204:207], v[188:191], v[64:67]
	v_mfma_f32_16x16x32_bf16 v[112:115], v[200:203], v[168:171], v[112:115]
	v_mfma_f32_16x16x32_bf16 v[104:107], v[212:215], v[168:171], v[104:107]
	v_mfma_f32_16x16x32_bf16 v[96:99], v[200:203], v[176:179], v[96:99]
	v_mfma_f32_16x16x32_bf16 v[88:91], v[212:215], v[176:179], v[88:91]
	v_mfma_f32_16x16x32_bf16 v[80:83], v[200:203], v[184:187], v[80:83]
	v_mfma_f32_16x16x32_bf16 v[72:75], v[212:215], v[184:187], v[72:75]
	v_mfma_f32_16x16x32_bf16 v[68:71], v[200:203], v[192:195], v[68:71]
	v_mfma_f32_16x16x32_bf16 v[64:67], v[212:215], v[192:195], v[64:67]
	s_setprio 0
	s_mov_b32 m0, s0
	v_lshl_add_u64 v[140:141], v[216:217], 0, s[2:3]
	s_barrier
	ds_read_b128 v[164:167], v146 offset:49152
	ds_read_b128 v[168:171], v146 offset:50176
	ds_read_b128 v[172:175], v146 offset:51200
	ds_read_b128 v[176:179], v146 offset:52224
	ds_read_b128 v[180:183], v146 offset:53248
	ds_read_b128 v[184:187], v146 offset:54272
	ds_read_b128 v[188:191], v146 offset:55296
	ds_read_b128 v[192:195], v146 offset:56320
	global_load_lds_dwordx4 v[140:141], off
	v_lshl_add_u64 v[140:141], v[218:219], 0, s[2:3]
	s_mov_b32 m0, s73
	s_nop 0
	global_load_lds_dwordx4 v[140:141], off
	s_barrier
	s_waitcnt lgkmcnt(0)
	s_setprio 1
	s_waitcnt lgkmcnt(0)
	v_mfma_f32_16x16x32_bf16 v[60:63], v[148:151], v[164:167], v[60:63]
	v_mfma_f32_16x16x32_bf16 v[56:59], v[156:159], v[164:167], v[56:59]
	v_mfma_f32_16x16x32_bf16 v[52:55], v[148:151], v[172:175], v[52:55]
	v_mfma_f32_16x16x32_bf16 v[44:47], v[156:159], v[172:175], v[44:47]
	v_mfma_f32_16x16x32_bf16 v[36:39], v[148:151], v[180:183], v[36:39]
	v_mfma_f32_16x16x32_bf16 v[28:31], v[156:159], v[180:183], v[28:31]
	v_mfma_f32_16x16x32_bf16 v[20:23], v[148:151], v[188:191], v[20:23]
	v_mfma_f32_16x16x32_bf16 v[12:15], v[156:159], v[188:191], v[12:15]
	v_mfma_f32_16x16x32_bf16 v[60:63], v[152:155], v[168:171], v[60:63]
	v_mfma_f32_16x16x32_bf16 v[56:59], v[160:163], v[168:171], v[56:59]
	v_mfma_f32_16x16x32_bf16 v[52:55], v[152:155], v[176:179], v[52:55]
	v_mfma_f32_16x16x32_bf16 v[44:47], v[160:163], v[176:179], v[44:47]
	v_mfma_f32_16x16x32_bf16 v[36:39], v[152:155], v[184:187], v[36:39]
	v_mfma_f32_16x16x32_bf16 v[28:31], v[160:163], v[184:187], v[28:31]
	v_mfma_f32_16x16x32_bf16 v[20:23], v[152:155], v[192:195], v[20:23]
	v_mfma_f32_16x16x32_bf16 v[12:15], v[160:163], v[192:195], v[12:15]
	s_setprio 0
	s_barrier
	s_add_u32 s48, s48, 0x40080
	s_addc_u32 s49, s49, 0
	s_add_i32 s50, s50, s69
	v_lshl_add_u64 v[140:141], s[48:49], 0, v[128:129]
	s_mov_b32 m0, s50
	s_nop 0
	global_load_lds_dwordx4 v[140:141], off
	v_lshl_add_u64 v[140:141], s[48:49], 0, v[134:135]
	s_add_i32 m0, s50, 0x2000
	s_nop 0
	global_load_lds_dwordx4 v[140:141], off
	s_waitcnt vmcnt(6)
	s_barrier
	s_setprio 1
	v_mfma_f32_16x16x32_bf16 v[48:51], v[196:199], v[164:167], v[48:51]
	v_mfma_f32_16x16x32_bf16 v[40:43], v[204:207], v[164:167], v[40:43]
	v_mfma_f32_16x16x32_bf16 v[32:35], v[196:199], v[172:175], v[32:35]
	v_mfma_f32_16x16x32_bf16 v[24:27], v[204:207], v[172:175], v[24:27]
	v_mfma_f32_16x16x32_bf16 v[16:19], v[196:199], v[180:183], v[16:19]
	v_mfma_f32_16x16x32_bf16 v[8:11], v[204:207], v[180:183], v[8:11]
	v_mfma_f32_16x16x32_bf16 v[4:7], v[196:199], v[188:191], v[4:7]
	v_mfma_f32_16x16x32_bf16 v[0:3], v[204:207], v[188:191], v[0:3]
	v_mfma_f32_16x16x32_bf16 v[48:51], v[200:203], v[168:171], v[48:51]
	v_mfma_f32_16x16x32_bf16 v[40:43], v[212:215], v[168:171], v[40:43]
	v_mfma_f32_16x16x32_bf16 v[32:35], v[200:203], v[176:179], v[32:35]
	v_mfma_f32_16x16x32_bf16 v[24:27], v[212:215], v[176:179], v[24:27]
	v_mfma_f32_16x16x32_bf16 v[16:19], v[200:203], v[184:187], v[16:19]
	v_mfma_f32_16x16x32_bf16 v[8:11], v[212:215], v[184:187], v[8:11]
	v_mfma_f32_16x16x32_bf16 v[4:7], v[200:203], v[192:195], v[4:7]
	v_mfma_f32_16x16x32_bf16 v[0:3], v[212:215], v[192:195], v[0:3]
	s_setprio 0
	s_add_i32 s80, s80, 2
	s_add_u32 s42, s42, 0x100
	s_addc_u32 s43, s43, 0
	s_add_u32 s78, s78, 0x100
	s_addc_u32 s79, s79, 0
	s_cmp_gt_u32 s80, 13
	s_barrier
	s_cbranch_scc0 .LBB0_200
	v_lshl_add_u32 v148, s36, 8, v143
	v_ashrrev_i32_e32 v149, 31, v148
	v_lshl_or_b32 v140, s75, 8, v145
	v_ashrrev_i32_e32 v141, 31, v140
	v_lshlrev_b64 v[150:151], 10, v[148:149]
	v_lshl_add_u64 v[150:151], s[14:15], 0, v[150:151]
	v_lshlrev_b64 v[152:153], 1, v[140:141]
	v_lshl_add_u64 v[140:141], v[150:151], 0, v[152:153]
	v_cvt_pk_bf16_f32 v124, v124, v125
	v_cvt_pk_bf16_f32 v125, v126, v127
	v_cvt_pk_bf16_f32 v126, v120, v121
	v_cvt_pk_bf16_f32 v127, v122, v123
	global_store_dwordx4 v[140:141], v[124:127], off nt
	v_cvt_pk_bf16_f32 v112, v112, v113
	v_cvt_pk_bf16_f32 v113, v114, v115
	v_cvt_pk_bf16_f32 v114, v104, v105
	v_or_b32_e32 v104, 16, v148
	v_ashrrev_i32_e32 v105, 31, v104
	v_lshlrev_b64 v[104:105], 10, v[104:105]
	v_lshl_add_u64 v[104:105], s[14:15], 0, v[104:105]
	v_cvt_pk_bf16_f32 v115, v106, v107
	global_store_dwordx4 v[140:141], v[112:115], off offset:256 nt
	s_mov_b32 s31, 0x20000
	s_mov_b64 s[42:43], 0x20000
	v_lshl_add_u64 v[112:113], v[104:105], 0, v[152:153]
	v_cvt_pk_bf16_f32 v104, v116, v117
	v_cvt_pk_bf16_f32 v105, v118, v119
	v_cvt_pk_bf16_f32 v106, v108, v109
	v_cvt_pk_bf16_f32 v107, v110, v111
	global_store_dwordx4 v[112:113], v[104:107], off nt
	v_cvt_pk_bf16_f32 v96, v96, v97
	v_cvt_pk_bf16_f32 v97, v98, v99
	v_cvt_pk_bf16_f32 v98, v88, v89
	v_or_b32_e32 v88, 32, v148
	v_ashrrev_i32_e32 v89, 31, v88
	v_lshlrev_b64 v[88:89], 10, v[88:89]
	v_lshl_add_u64 v[88:89], s[14:15], 0, v[88:89]
	v_cvt_pk_bf16_f32 v99, v90, v91
	global_store_dwordx4 v[112:113], v[96:99], off offset:256 nt
	s_mov_b32 s75, s30
	s_mov_b32 s36, s34
	v_lshl_add_u64 v[96:97], v[88:89], 0, v[152:153]
	v_cvt_pk_bf16_f32 v88, v100, v101
	v_cvt_pk_bf16_f32 v89, v102, v103
	v_cvt_pk_bf16_f32 v90, v92, v93
	v_cvt_pk_bf16_f32 v91, v94, v95
	global_store_dwordx4 v[96:97], v[88:91], off nt
	v_cvt_pk_bf16_f32 v80, v80, v81
	v_cvt_pk_bf16_f32 v81, v82, v83
	v_cvt_pk_bf16_f32 v82, v72, v73
	v_or_b32_e32 v72, 48, v148
	v_ashrrev_i32_e32 v73, 31, v72
	v_lshlrev_b64 v[72:73], 10, v[72:73]
	v_lshl_add_u64 v[72:73], s[14:15], 0, v[72:73]
	v_cvt_pk_bf16_f32 v83, v74, v75
	global_store_dwordx4 v[96:97], v[80:83], off offset:256 nt
	s_mov_b64 s[48:49], s[40:41]
	s_nop 0
	v_lshl_add_u64 v[80:81], v[72:73], 0, v[152:153]
	v_cvt_pk_bf16_f32 v72, v84, v85
	v_cvt_pk_bf16_f32 v73, v86, v87
	v_cvt_pk_bf16_f32 v74, v76, v77
	v_cvt_pk_bf16_f32 v75, v78, v79
	global_store_dwordx4 v[80:81], v[72:75], off nt
	v_cvt_pk_bf16_f32 v68, v68, v69
	v_cvt_pk_bf16_f32 v69, v70, v71
	v_cvt_pk_bf16_f32 v70, v64, v65
	v_cvt_pk_bf16_f32 v71, v66, v67
	global_store_dwordx4 v[80:81], v[68:71], off offset:256 nt
	v_cvt_pk_bf16_f32 v60, v60, v61
	v_cvt_pk_bf16_f32 v61, v62, v63
	v_cvt_pk_bf16_f32 v62, v56, v57
	v_add_co_u32_e32 v56, vcc, s31, v140
	v_lshl_add_u64 v[64:65], v[140:141], 0, s[42:43]
	s_nop 0
	v_addc_co_u32_e32 v57, vcc, 0, v141, vcc
	s_mov_b32 s31, 0x24000
	v_cvt_pk_bf16_f32 v63, v58, v59
	global_store_dwordx4 v[56:57], v[60:63], off nt
	v_cvt_pk_bf16_f32 v48, v48, v49
	v_cvt_pk_bf16_f32 v49, v50, v51
	v_cvt_pk_bf16_f32 v50, v40, v41
	v_cvt_pk_bf16_f32 v51, v42, v43
	global_store_dwordx4 v[64:65], v[48:51], off offset:256 nt
	s_mov_b64 s[42:43], 0x24000
	v_cvt_pk_bf16_f32 v40, v52, v53
	v_cvt_pk_bf16_f32 v41, v54, v55
	v_cvt_pk_bf16_f32 v42, v44, v45
	v_add_co_u32_e32 v44, vcc, s31, v140
	v_lshl_add_u64 v[48:49], v[140:141], 0, s[42:43]
	s_nop 0
	v_addc_co_u32_e32 v45, vcc, 0, v141, vcc
	s_mov_b32 s31, 0x28000
	v_cvt_pk_bf16_f32 v43, v46, v47
	global_store_dwordx4 v[44:45], v[40:43], off nt
	v_cvt_pk_bf16_f32 v32, v32, v33
	v_cvt_pk_bf16_f32 v33, v34, v35
	v_cvt_pk_bf16_f32 v34, v24, v25
	v_cvt_pk_bf16_f32 v35, v26, v27
	global_store_dwordx4 v[48:49], v[32:35], off offset:256 nt
	s_mov_b64 s[42:43], 0x28000
	v_cvt_pk_bf16_f32 v24, v36, v37
	v_cvt_pk_bf16_f32 v25, v38, v39
	v_cvt_pk_bf16_f32 v26, v28, v29
	v_add_co_u32_e32 v28, vcc, s31, v140
	v_lshl_add_u64 v[32:33], v[140:141], 0, s[42:43]
	s_nop 0
	v_addc_co_u32_e32 v29, vcc, 0, v141, vcc
	s_mov_b32 s31, 0x2c000
	v_cvt_pk_bf16_f32 v27, v30, v31
	global_store_dwordx4 v[28:29], v[24:27], off nt
	v_cvt_pk_bf16_f32 v16, v16, v17
	v_cvt_pk_bf16_f32 v17, v18, v19
	v_cvt_pk_bf16_f32 v18, v8, v9
	v_cvt_pk_bf16_f32 v19, v10, v11
	global_store_dwordx4 v[32:33], v[16:19], off offset:256 nt
	v_cvt_pk_bf16_f32 v8, v20, v21
	v_cvt_pk_bf16_f32 v9, v22, v23
	v_cvt_pk_bf16_f32 v10, v12, v13
	v_add_co_u32_e32 v12, vcc, s31, v140
	s_mov_b64 s[42:43], 0x2c000
	s_nop 0
	v_addc_co_u32_e32 v13, vcc, 0, v141, vcc
	v_lshl_add_u64 v[16:17], v[140:141], 0, s[42:43]
	s_and_b64 vcc, exec, s[28:29]
	s_mov_b64 s[42:43], s[38:39]
	v_cvt_pk_bf16_f32 v11, v14, v15
	global_store_dwordx4 v[12:13], v[8:11], off nt
	v_cvt_pk_bf16_f32 v4, v4, v5
	v_cvt_pk_bf16_f32 v5, v6, v7
	v_cvt_pk_bf16_f32 v6, v0, v1
	v_cvt_pk_bf16_f32 v7, v2, v3
	global_store_dwordx4 v[16:17], v[4:7], off offset:256 nt
	s_cbranch_vccz .LBB0_193
	s_waitcnt vmcnt(0)
	s_cmpk_gt_u32 s65, 0xff
	s_cbranch_scc1 .LBB0_204
	s_barrier

.LBB0_220:
	s_add_u32 s40, s38, 0xfffc0080
	s_addc_u32 s41, s39, -1
	s_add_i32 s76, 0, 0x10000
	v_add_u32_e32 v140, s76, v144
	ds_read_b128 v[148:151], v140
	ds_read_b128 v[152:155], v140 offset:1024
	ds_read_b128 v[156:159], v140 offset:2048
	ds_read_b128 v[160:163], v140 offset:3072
	s_cmp_eq_u32 s75, 12
	s_cselect_b32 s43, s29, s41
	s_cselect_b32 s42, s71, s40
	s_cselect_b32 s41, s15, s74
	s_cselect_b32 s40, s72, s73
	v_lshl_add_u64 v[140:141], s[38:39], 0, v[136:137]
	s_add_i32 m0, s31, 0xc000
	ds_read_b128 v[164:167], v146
	ds_read_b128 v[168:171], v146 offset:1024
	ds_read_b128 v[172:175], v146 offset:2048
	ds_read_b128 v[176:179], v146 offset:3072
	ds_read_b128 v[180:183], v146 offset:4096
	ds_read_b128 v[184:187], v146 offset:5120
	ds_read_b128 v[188:191], v146 offset:6144
	ds_read_b128 v[192:195], v146 offset:7168
	global_load_lds_dwordx4 v[140:141], off
	v_lshl_add_u64 v[140:141], s[38:39], 0, v[138:139]
	s_add_i32 m0, s31, 0xe000
	s_nop 0
	global_load_lds_dwordx4 v[140:141], off
	s_waitcnt lgkmcnt(8)
	s_barrier
	s_waitcnt lgkmcnt(0)
	s_setprio 1
	s_waitcnt lgkmcnt(0)
	v_mfma_f32_16x16x32_bf16 v[124:127], v[148:151], v[164:167], v[124:127]
	v_mfma_f32_16x16x32_bf16 v[120:123], v[156:159], v[164:167], v[120:123]
	v_mfma_f32_16x16x32_bf16 v[116:119], v[148:151], v[172:175], v[116:119]
	v_mfma_f32_16x16x32_bf16 v[108:111], v[156:159], v[172:175], v[108:111]
	v_mfma_f32_16x16x32_bf16 v[100:103], v[148:151], v[180:183], v[100:103]
	v_mfma_f32_16x16x32_bf16 v[92:95], v[156:159], v[180:183], v[92:95]
	v_mfma_f32_16x16x32_bf16 v[84:87], v[148:151], v[188:191], v[84:87]
	v_mfma_f32_16x16x32_bf16 v[76:79], v[156:159], v[188:191], v[76:79]
	v_mfma_f32_16x16x32_bf16 v[124:127], v[152:155], v[168:171], v[124:127]
	v_mfma_f32_16x16x32_bf16 v[120:123], v[160:163], v[168:171], v[120:123]
	v_mfma_f32_16x16x32_bf16 v[116:119], v[152:155], v[176:179], v[116:119]
	v_mfma_f32_16x16x32_bf16 v[108:111], v[160:163], v[176:179], v[108:111]
	v_mfma_f32_16x16x32_bf16 v[100:103], v[152:155], v[184:187], v[100:103]
	v_mfma_f32_16x16x32_bf16 v[92:95], v[160:163], v[184:187], v[92:95]
	v_mfma_f32_16x16x32_bf16 v[84:87], v[152:155], v[192:195], v[84:87]
	v_mfma_f32_16x16x32_bf16 v[76:79], v[160:163], v[192:195], v[76:79]
	s_setprio 0
	s_barrier
	s_add_i32 s78, 0, 0x14000
	v_add_u32_e32 v140, s78, v144
	s_add_i32 s76, s76, s64
	ds_read_b128 v[196:199], v140
	ds_read_b128 v[200:203], v140 offset:1024
	ds_read_b128 v[204:207], v140 offset:2048
	ds_read_b128 v[212:215], v140 offset:3072
	v_lshl_add_u64 v[140:141], s[40:41], 0, v[128:129]
	s_mov_b32 m0, s76
	v_lshl_add_u64 v[208:209], s[40:41], 0, v[134:135]
	global_load_lds_dwordx4 v[140:141], off
	s_add_i32 m0, s76, 0x2000
	s_nop 0
	global_load_lds_dwordx4 v[208:209], off
	s_barrier
	s_waitcnt lgkmcnt(0)
	s_setprio 1
	s_waitcnt lgkmcnt(0)
	v_mfma_f32_16x16x32_bf16 v[112:115], v[196:199], v[164:167], v[112:115]
	v_mfma_f32_16x16x32_bf16 v[104:107], v[204:207], v[164:167], v[104:107]
	v_mfma_f32_16x16x32_bf16 v[96:99], v[196:199], v[172:175], v[96:99]
	v_mfma_f32_16x16x32_bf16 v[88:91], v[204:207], v[172:175], v[88:91]
	v_mfma_f32_16x16x32_bf16 v[80:83], v[196:199], v[180:183], v[80:83]
	v_mfma_f32_16x16x32_bf16 v[72:75], v[204:207], v[180:183], v[72:75]
	v_mfma_f32_16x16x32_bf16 v[68:71], v[196:199], v[188:191], v[68:71]
	v_mfma_f32_16x16x32_bf16 v[64:67], v[204:207], v[188:191], v[64:67]
	v_mfma_f32_16x16x32_bf16 v[112:115], v[200:203], v[168:171], v[112:115]
	v_mfma_f32_16x16x32_bf16 v[104:107], v[212:215], v[168:171], v[104:107]
	v_mfma_f32_16x16x32_bf16 v[96:99], v[200:203], v[176:179], v[96:99]
	v_mfma_f32_16x16x32_bf16 v[88:91], v[212:215], v[176:179], v[88:91]
	v_mfma_f32_16x16x32_bf16 v[80:83], v[200:203], v[184:187], v[80:83]
	v_mfma_f32_16x16x32_bf16 v[72:75], v[212:215], v[184:187], v[72:75]
	v_mfma_f32_16x16x32_bf16 v[68:71], v[200:203], v[192:195], v[68:71]
	v_mfma_f32_16x16x32_bf16 v[64:67], v[212:215], v[192:195], v[64:67]
	s_setprio 0
	s_mov_b32 m0, s31
	v_lshl_add_u64 v[216:217], s[42:43], 0, v[130:131]
	s_barrier
	ds_read_b128 v[164:167], v146 offset:16384
	ds_read_b128 v[168:171], v146 offset:17408
	ds_read_b128 v[172:175], v146 offset:18432
	ds_read_b128 v[176:179], v146 offset:19456
	ds_read_b128 v[180:183], v146 offset:20480
	ds_read_b128 v[184:187], v146 offset:21504
	ds_read_b128 v[188:191], v146 offset:22528
	ds_read_b128 v[192:195], v146 offset:23552
	global_load_lds_dwordx4 v[216:217], off
	v_lshl_add_u64 v[218:219], s[42:43], 0, v[132:133]
	s_mov_b32 m0, s65
	s_nop 0
	global_load_lds_dwordx4 v[218:219], off
	s_barrier
	s_waitcnt lgkmcnt(0)
	s_setprio 1
	s_waitcnt lgkmcnt(0)
	v_mfma_f32_16x16x32_bf16 v[60:63], v[148:151], v[164:167], v[60:63]
	v_mfma_f32_16x16x32_bf16 v[56:59], v[156:159], v[164:167], v[56:59]
	v_mfma_f32_16x16x32_bf16 v[52:55], v[148:151], v[172:175], v[52:55]
	v_mfma_f32_16x16x32_bf16 v[44:47], v[156:159], v[172:175], v[44:47]
	v_mfma_f32_16x16x32_bf16 v[36:39], v[148:151], v[180:183], v[36:39]
	v_mfma_f32_16x16x32_bf16 v[28:31], v[156:159], v[180:183], v[28:31]
	v_mfma_f32_16x16x32_bf16 v[20:23], v[148:151], v[188:191], v[20:23]
	v_mfma_f32_16x16x32_bf16 v[12:15], v[156:159], v[188:191], v[12:15]
	v_mfma_f32_16x16x32_bf16 v[60:63], v[152:155], v[168:171], v[60:63]
	v_mfma_f32_16x16x32_bf16 v[56:59], v[160:163], v[168:171], v[56:59]
	v_mfma_f32_16x16x32_bf16 v[52:55], v[152:155], v[176:179], v[52:55]
	v_mfma_f32_16x16x32_bf16 v[44:47], v[160:163], v[176:179], v[44:47]
	v_mfma_f32_16x16x32_bf16 v[36:39], v[152:155], v[184:187], v[36:39]
	v_mfma_f32_16x16x32_bf16 v[28:31], v[160:163], v[184:187], v[28:31]
	v_mfma_f32_16x16x32_bf16 v[20:23], v[152:155], v[192:195], v[20:23]
	v_mfma_f32_16x16x32_bf16 v[12:15], v[160:163], v[192:195], v[12:15]
	s_setprio 0
	s_barrier
	s_add_u32 s76, s40, 0x40000
	s_addc_u32 s77, s41, 0
	s_add_i32 s78, s78, s64
	v_lshl_add_u64 v[148:149], s[76:77], 0, v[128:129]
	s_mov_b32 m0, s78
	s_nop 0
	global_load_lds_dwordx4 v[148:149], off
	v_lshl_add_u64 v[148:149], s[76:77], 0, v[134:135]
	s_add_i32 m0, s78, 0x2000
	s_nop 0
	global_load_lds_dwordx4 v[148:149], off
	s_waitcnt vmcnt(6)
	s_barrier
	s_setprio 1
	v_mfma_f32_16x16x32_bf16 v[48:51], v[196:199], v[164:167], v[48:51]
	v_mfma_f32_16x16x32_bf16 v[40:43], v[204:207], v[164:167], v[40:43]
	v_mfma_f32_16x16x32_bf16 v[32:35], v[196:199], v[172:175], v[32:35]
	v_mfma_f32_16x16x32_bf16 v[24:27], v[204:207], v[172:175], v[24:27]
	v_mfma_f32_16x16x32_bf16 v[16:19], v[196:199], v[180:183], v[16:19]
	v_mfma_f32_16x16x32_bf16 v[8:11], v[204:207], v[180:183], v[8:11]
	v_mfma_f32_16x16x32_bf16 v[4:7], v[196:199], v[188:191], v[4:7]
	v_mfma_f32_16x16x32_bf16 v[0:3], v[204:207], v[188:191], v[0:3]
	v_mfma_f32_16x16x32_bf16 v[48:51], v[200:203], v[168:171], v[48:51]
	v_mfma_f32_16x16x32_bf16 v[40:43], v[212:215], v[168:171], v[40:43]
	v_mfma_f32_16x16x32_bf16 v[32:35], v[200:203], v[176:179], v[32:35]
	v_mfma_f32_16x16x32_bf16 v[24:27], v[212:215], v[176:179], v[24:27]
	v_mfma_f32_16x16x32_bf16 v[16:19], v[200:203], v[184:187], v[16:19]
	v_mfma_f32_16x16x32_bf16 v[8:11], v[212:215], v[184:187], v[8:11]
	v_mfma_f32_16x16x32_bf16 v[4:7], v[200:203], v[192:195], v[4:7]
	v_mfma_f32_16x16x32_bf16 v[0:3], v[212:215], v[192:195], v[0:3]
	s_setprio 0
	s_add_i32 s76, 0, 0x18000
	v_add_u32_e32 v147, s76, v144
	s_barrier
	ds_read_b128 v[148:151], v147
	ds_read_b128 v[152:155], v147 offset:1024
	ds_read_b128 v[156:159], v147 offset:2048
	ds_read_b128 v[160:163], v147 offset:3072
	s_add_u32 s42, s42, 0x40000
	s_addc_u32 s43, s43, 0
	s_mov_b32 m0, s66
	v_lshl_add_u64 v[196:197], s[42:43], 0, v[130:131]
	ds_read_b128 v[164:167], v146 offset:32768
	ds_read_b128 v[168:171], v146 offset:33792
	ds_read_b128 v[172:175], v146 offset:34816
	ds_read_b128 v[176:179], v146 offset:35840
	ds_read_b128 v[180:183], v146 offset:36864
	ds_read_b128 v[184:187], v146 offset:37888
	ds_read_b128 v[188:191], v146 offset:38912
	ds_read_b128 v[192:195], v146 offset:39936
	global_load_lds_dwordx4 v[196:197], off
	v_lshl_add_u64 v[196:197], s[42:43], 0, v[132:133]
	s_mov_b32 m0, s67
	s_nop 0
	global_load_lds_dwordx4 v[196:197], off
	s_waitcnt lgkmcnt(8)
	s_barrier
	s_waitcnt lgkmcnt(0)
	s_setprio 1
	s_waitcnt lgkmcnt(0)
	v_mfma_f32_16x16x32_bf16 v[124:127], v[148:151], v[164:167], v[124:127]
	v_mfma_f32_16x16x32_bf16 v[120:123], v[156:159], v[164:167], v[120:123]
	v_mfma_f32_16x16x32_bf16 v[116:119], v[148:151], v[172:175], v[116:119]
	v_mfma_f32_16x16x32_bf16 v[108:111], v[156:159], v[172:175], v[108:111]
	v_mfma_f32_16x16x32_bf16 v[100:103], v[148:151], v[180:183], v[100:103]
	v_mfma_f32_16x16x32_bf16 v[92:95], v[156:159], v[180:183], v[92:95]
	v_mfma_f32_16x16x32_bf16 v[84:87], v[148:151], v[188:191], v[84:87]
	v_mfma_f32_16x16x32_bf16 v[76:79], v[156:159], v[188:191], v[76:79]
	v_mfma_f32_16x16x32_bf16 v[124:127], v[152:155], v[168:171], v[124:127]
	v_mfma_f32_16x16x32_bf16 v[120:123], v[160:163], v[168:171], v[120:123]
	v_mfma_f32_16x16x32_bf16 v[116:119], v[152:155], v[176:179], v[116:119]
	v_mfma_f32_16x16x32_bf16 v[108:111], v[160:163], v[176:179], v[108:111]
	v_mfma_f32_16x16x32_bf16 v[100:103], v[152:155], v[184:187], v[100:103]
	v_mfma_f32_16x16x32_bf16 v[92:95], v[160:163], v[184:187], v[92:95]
	v_mfma_f32_16x16x32_bf16 v[84:87], v[152:155], v[192:195], v[84:87]
	v_mfma_f32_16x16x32_bf16 v[76:79], v[160:163], v[192:195], v[76:79]
	s_setprio 0
	s_barrier
	s_add_i32 s42, 0, 0x1c000
	s_add_i32 s43, s76, s64
	v_add_u32_e32 v147, s42, v144
	v_lshl_add_u64 v[140:141], v[140:141], 0, s[2:3]
	s_mov_b32 m0, s43
	ds_read_b128 v[196:199], v147
	ds_read_b128 v[200:203], v147 offset:1024
	ds_read_b128 v[204:207], v147 offset:2048
	ds_read_b128 v[212:215], v147 offset:3072
	global_load_lds_dwordx4 v[140:141], off
	v_lshl_add_u64 v[140:141], v[208:209], 0, s[2:3]
	s_add_i32 m0, s43, 0x2000
	s_nop 0
	global_load_lds_dwordx4 v[140:141], off
	s_barrier
	s_waitcnt lgkmcnt(0)
	s_setprio 1
	s_waitcnt lgkmcnt(0)
	v_mfma_f32_16x16x32_bf16 v[112:115], v[196:199], v[164:167], v[112:115]
	v_mfma_f32_16x16x32_bf16 v[104:107], v[204:207], v[164:167], v[104:107]
	v_mfma_f32_16x16x32_bf16 v[96:99], v[196:199], v[172:175], v[96:99]
	v_mfma_f32_16x16x32_bf16 v[88:91], v[204:207], v[172:175], v[88:91]
	v_mfma_f32_16x16x32_bf16 v[80:83], v[196:199], v[180:183], v[80:83]
	v_mfma_f32_16x16x32_bf16 v[72:75], v[204:207], v[180:183], v[72:75]
	v_mfma_f32_16x16x32_bf16 v[68:71], v[196:199], v[188:191], v[68:71]
	v_mfma_f32_16x16x32_bf16 v[64:67], v[204:207], v[188:191], v[64:67]
	v_mfma_f32_16x16x32_bf16 v[112:115], v[200:203], v[168:171], v[112:115]
	v_mfma_f32_16x16x32_bf16 v[104:107], v[212:215], v[168:171], v[104:107]
	v_mfma_f32_16x16x32_bf16 v[96:99], v[200:203], v[176:179], v[96:99]
	v_mfma_f32_16x16x32_bf16 v[88:91], v[212:215], v[176:179], v[88:91]
	v_mfma_f32_16x16x32_bf16 v[80:83], v[200:203], v[184:187], v[80:83]
	v_mfma_f32_16x16x32_bf16 v[72:75], v[212:215], v[184:187], v[72:75]
	v_mfma_f32_16x16x32_bf16 v[68:71], v[200:203], v[192:195], v[68:71]
	v_mfma_f32_16x16x32_bf16 v[64:67], v[212:215], v[192:195], v[64:67]
	s_setprio 0
	s_mov_b32 m0, s0
	v_lshl_add_u64 v[140:141], v[216:217], 0, s[2:3]
	s_barrier
	ds_read_b128 v[164:167], v146 offset:49152
	ds_read_b128 v[168:171], v146 offset:50176
	ds_read_b128 v[172:175], v146 offset:51200
	ds_read_b128 v[176:179], v146 offset:52224
	ds_read_b128 v[180:183], v146 offset:53248
	ds_read_b128 v[184:187], v146 offset:54272
	ds_read_b128 v[188:191], v146 offset:55296
	ds_read_b128 v[192:195], v146 offset:56320
	global_load_lds_dwordx4 v[140:141], off
	v_lshl_add_u64 v[140:141], v[218:219], 0, s[2:3]
	s_mov_b32 m0, s68
	s_nop 0
	global_load_lds_dwordx4 v[140:141], off
	s_barrier
	s_waitcnt lgkmcnt(0)
	s_setprio 1
	s_waitcnt lgkmcnt(0)
	v_mfma_f32_16x16x32_bf16 v[60:63], v[148:151], v[164:167], v[60:63]
	v_mfma_f32_16x16x32_bf16 v[56:59], v[156:159], v[164:167], v[56:59]
	v_mfma_f32_16x16x32_bf16 v[52:55], v[148:151], v[172:175], v[52:55]
	v_mfma_f32_16x16x32_bf16 v[44:47], v[156:159], v[172:175], v[44:47]
	v_mfma_f32_16x16x32_bf16 v[36:39], v[148:151], v[180:183], v[36:39]
	v_mfma_f32_16x16x32_bf16 v[28:31], v[156:159], v[180:183], v[28:31]
	v_mfma_f32_16x16x32_bf16 v[20:23], v[148:151], v[188:191], v[20:23]
	v_mfma_f32_16x16x32_bf16 v[12:15], v[156:159], v[188:191], v[12:15]
	v_mfma_f32_16x16x32_bf16 v[60:63], v[152:155], v[168:171], v[60:63]
	v_mfma_f32_16x16x32_bf16 v[56:59], v[160:163], v[168:171], v[56:59]
	v_mfma_f32_16x16x32_bf16 v[52:55], v[152:155], v[176:179], v[52:55]
	v_mfma_f32_16x16x32_bf16 v[44:47], v[160:163], v[176:179], v[44:47]
	v_mfma_f32_16x16x32_bf16 v[36:39], v[152:155], v[184:187], v[36:39]
	v_mfma_f32_16x16x32_bf16 v[28:31], v[160:163], v[184:187], v[28:31]
	v_mfma_f32_16x16x32_bf16 v[20:23], v[152:155], v[192:195], v[20:23]
	v_mfma_f32_16x16x32_bf16 v[12:15], v[160:163], v[192:195], v[12:15]
	s_setprio 0
	s_barrier
	s_add_u32 s40, s40, 0x40080
	s_addc_u32 s41, s41, 0
	s_add_i32 s42, s42, s64
	v_lshl_add_u64 v[140:141], s[40:41], 0, v[128:129]
	s_mov_b32 m0, s42
	s_nop 0
	global_load_lds_dwordx4 v[140:141], off
	v_lshl_add_u64 v[140:141], s[40:41], 0, v[134:135]
	s_add_i32 m0, s42, 0x2000
	s_nop 0
	global_load_lds_dwordx4 v[140:141], off
	s_waitcnt vmcnt(6)
	s_barrier
	s_setprio 1
	v_mfma_f32_16x16x32_bf16 v[48:51], v[196:199], v[164:167], v[48:51]
	v_mfma_f32_16x16x32_bf16 v[40:43], v[204:207], v[164:167], v[40:43]
	v_mfma_f32_16x16x32_bf16 v[32:35], v[196:199], v[172:175], v[32:35]
	v_mfma_f32_16x16x32_bf16 v[24:27], v[204:207], v[172:175], v[24:27]
	v_mfma_f32_16x16x32_bf16 v[16:19], v[196:199], v[180:183], v[16:19]
	v_mfma_f32_16x16x32_bf16 v[8:11], v[204:207], v[180:183], v[8:11]
	v_mfma_f32_16x16x32_bf16 v[4:7], v[196:199], v[188:191], v[4:7]
	v_mfma_f32_16x16x32_bf16 v[0:3], v[204:207], v[188:191], v[0:3]
	v_mfma_f32_16x16x32_bf16 v[48:51], v[200:203], v[168:171], v[48:51]
	v_mfma_f32_16x16x32_bf16 v[40:43], v[212:215], v[168:171], v[40:43]
	v_mfma_f32_16x16x32_bf16 v[32:35], v[200:203], v[176:179], v[32:35]
	v_mfma_f32_16x16x32_bf16 v[24:27], v[212:215], v[176:179], v[24:27]
	v_mfma_f32_16x16x32_bf16 v[16:19], v[200:203], v[184:187], v[16:19]
	v_mfma_f32_16x16x32_bf16 v[8:11], v[212:215], v[184:187], v[8:11]
	v_mfma_f32_16x16x32_bf16 v[4:7], v[200:203], v[192:195], v[4:7]
	v_mfma_f32_16x16x32_bf16 v[0:3], v[212:215], v[192:195], v[0:3]
	s_setprio 0
	s_add_i32 s75, s75, 2
	s_add_u32 s38, s38, 0x100
	s_addc_u32 s39, s39, 0
	s_add_u32 s73, s73, 0x100
	s_addc_u32 s74, s74, 0
	s_cmp_gt_u32 s75, 13
	s_barrier
	s_cbranch_scc0 .LBB0_220
	v_lshl_add_u32 v148, s30, 8, v143
	v_ashrrev_i32_e32 v149, 31, v148
	v_lshl_or_b32 v140, s70, 8, v145
	v_ashrrev_i32_e32 v141, 31, v140
	v_lshlrev_b64 v[150:151], 13, v[148:149]
	v_lshl_add_u64 v[150:151], s[8:9], 0, v[150:151]
	v_lshlrev_b64 v[152:153], 1, v[140:141]
	v_lshl_add_u64 v[140:141], v[150:151], 0, v[152:153]
	v_cvt_pk_bf16_f32 v124, v124, v125
	v_cvt_pk_bf16_f32 v125, v126, v127
	v_cvt_pk_bf16_f32 v126, v120, v121
	v_cvt_pk_bf16_f32 v127, v122, v123
	global_store_dwordx4 v[140:141], v[124:127], off nt
	v_cvt_pk_bf16_f32 v112, v112, v113
	v_cvt_pk_bf16_f32 v113, v114, v115
	v_cvt_pk_bf16_f32 v114, v104, v105
	v_or_b32_e32 v104, 16, v148
	v_ashrrev_i32_e32 v105, 31, v104
	v_lshlrev_b64 v[104:105], 13, v[104:105]
	v_lshl_add_u64 v[104:105], s[8:9], 0, v[104:105]
	v_cvt_pk_bf16_f32 v115, v106, v107
	global_store_dwordx4 v[140:141], v[112:115], off offset:256 nt
	s_mov_b32 s15, 0x100000
	s_mov_b64 s[38:39], 0x100000
	v_lshl_add_u64 v[112:113], v[104:105], 0, v[152:153]
	v_cvt_pk_bf16_f32 v104, v116, v117
	v_cvt_pk_bf16_f32 v105, v118, v119
	v_cvt_pk_bf16_f32 v106, v108, v109
	v_cvt_pk_bf16_f32 v107, v110, v111
	global_store_dwordx4 v[112:113], v[104:107], off nt
	v_cvt_pk_bf16_f32 v96, v96, v97
	v_cvt_pk_bf16_f32 v97, v98, v99
	v_cvt_pk_bf16_f32 v98, v88, v89
	v_or_b32_e32 v88, 32, v148
	v_ashrrev_i32_e32 v89, 31, v88
	v_lshlrev_b64 v[88:89], 13, v[88:89]
	v_lshl_add_u64 v[88:89], s[8:9], 0, v[88:89]
	v_cvt_pk_bf16_f32 v99, v90, v91
	global_store_dwordx4 v[112:113], v[96:99], off offset:256 nt
	s_mov_b32 s70, s14
	s_mov_b32 s30, s28
	v_lshl_add_u64 v[96:97], v[88:89], 0, v[152:153]
	v_cvt_pk_bf16_f32 v88, v100, v101
	v_cvt_pk_bf16_f32 v89, v102, v103
	v_cvt_pk_bf16_f32 v90, v92, v93
	v_cvt_pk_bf16_f32 v91, v94, v95
	global_store_dwordx4 v[96:97], v[88:91], off nt
	v_cvt_pk_bf16_f32 v80, v80, v81
	v_cvt_pk_bf16_f32 v81, v82, v83
	v_cvt_pk_bf16_f32 v82, v72, v73
	v_or_b32_e32 v72, 48, v148
	v_ashrrev_i32_e32 v73, 31, v72
	v_lshlrev_b64 v[72:73], 13, v[72:73]
	v_lshl_add_u64 v[72:73], s[8:9], 0, v[72:73]
	v_cvt_pk_bf16_f32 v83, v74, v75
	global_store_dwordx4 v[96:97], v[80:83], off offset:256 nt
	s_mov_b64 s[40:41], s[36:37]
	s_nop 0
	v_lshl_add_u64 v[80:81], v[72:73], 0, v[152:153]
	v_cvt_pk_bf16_f32 v72, v84, v85
	v_cvt_pk_bf16_f32 v73, v86, v87
	v_cvt_pk_bf16_f32 v74, v76, v77
	v_cvt_pk_bf16_f32 v75, v78, v79
	global_store_dwordx4 v[80:81], v[72:75], off nt
	v_cvt_pk_bf16_f32 v68, v68, v69
	v_cvt_pk_bf16_f32 v69, v70, v71
	v_cvt_pk_bf16_f32 v70, v64, v65
	v_cvt_pk_bf16_f32 v71, v66, v67
	global_store_dwordx4 v[80:81], v[68:71], off offset:256 nt
	v_cvt_pk_bf16_f32 v60, v60, v61
	v_cvt_pk_bf16_f32 v61, v62, v63
	v_cvt_pk_bf16_f32 v62, v56, v57
	v_add_co_u32_e32 v56, vcc, s15, v140
	v_lshl_add_u64 v[64:65], v[140:141], 0, s[38:39]
	s_nop 0
	v_addc_co_u32_e32 v57, vcc, 0, v141, vcc
	s_mov_b32 s15, 0x120000
	v_cvt_pk_bf16_f32 v63, v58, v59
	global_store_dwordx4 v[56:57], v[60:63], off nt
	v_cvt_pk_bf16_f32 v48, v48, v49
	v_cvt_pk_bf16_f32 v49, v50, v51
	v_cvt_pk_bf16_f32 v50, v40, v41
	v_cvt_pk_bf16_f32 v51, v42, v43
	global_store_dwordx4 v[64:65], v[48:51], off offset:256 nt
	s_mov_b64 s[38:39], 0x120000
	v_cvt_pk_bf16_f32 v40, v52, v53
	v_cvt_pk_bf16_f32 v41, v54, v55
	v_cvt_pk_bf16_f32 v42, v44, v45
	v_add_co_u32_e32 v44, vcc, s15, v140
	v_lshl_add_u64 v[48:49], v[140:141], 0, s[38:39]
	s_nop 0
	v_addc_co_u32_e32 v45, vcc, 0, v141, vcc
	s_mov_b32 s15, 0x140000
	v_cvt_pk_bf16_f32 v43, v46, v47
	global_store_dwordx4 v[44:45], v[40:43], off nt
	v_cvt_pk_bf16_f32 v32, v32, v33
	v_cvt_pk_bf16_f32 v33, v34, v35
	v_cvt_pk_bf16_f32 v34, v24, v25
	v_cvt_pk_bf16_f32 v35, v26, v27
	global_store_dwordx4 v[48:49], v[32:35], off offset:256 nt
	s_mov_b64 s[38:39], 0x140000
	v_cvt_pk_bf16_f32 v24, v36, v37
	v_cvt_pk_bf16_f32 v25, v38, v39
	v_cvt_pk_bf16_f32 v26, v28, v29
	v_add_co_u32_e32 v28, vcc, s15, v140
	v_lshl_add_u64 v[32:33], v[140:141], 0, s[38:39]
	s_nop 0
	v_addc_co_u32_e32 v29, vcc, 0, v141, vcc
	s_mov_b32 s15, 0x160000
	v_cvt_pk_bf16_f32 v27, v30, v31
	global_store_dwordx4 v[28:29], v[24:27], off nt
	v_cvt_pk_bf16_f32 v16, v16, v17
	v_cvt_pk_bf16_f32 v17, v18, v19
	v_cvt_pk_bf16_f32 v18, v8, v9
	v_cvt_pk_bf16_f32 v19, v10, v11
	global_store_dwordx4 v[32:33], v[16:19], off offset:256 nt
	v_cvt_pk_bf16_f32 v8, v20, v21
	v_cvt_pk_bf16_f32 v9, v22, v23
	v_cvt_pk_bf16_f32 v10, v12, v13
	v_add_co_u32_e32 v12, vcc, s15, v140
	s_mov_b64 s[38:39], 0x160000
	s_nop 0
	v_addc_co_u32_e32 v13, vcc, 0, v141, vcc
	v_lshl_add_u64 v[16:17], v[140:141], 0, s[38:39]
	s_and_b64 vcc, exec, s[12:13]
	s_mov_b64 s[38:39], s[34:35]
	v_cvt_pk_bf16_f32 v11, v14, v15
	global_store_dwordx4 v[12:13], v[8:11], off nt
	v_cvt_pk_bf16_f32 v4, v4, v5
	v_cvt_pk_bf16_f32 v5, v6, v7
	v_cvt_pk_bf16_f32 v6, v0, v1
	v_cvt_pk_bf16_f32 v7, v2, v3
	global_store_dwordx4 v[16:17], v[4:7], off offset:256 nt
	s_cbranch_vccz .LBB0_213
	s_waitcnt vmcnt(0)
	s_cmpk_gt_u32 s49, 0xff
	s_cbranch_scc1 .LBB0_183
	s_barrier
	s_branch .LBB0_183

.LBB0_946:
	ds_read_b128 v[144:147], v153
	ds_read_b128 v[158:161], v153 offset:1024
	ds_read_b128 v[162:165], v153 offset:2048
	ds_read_b128 v[166:169], v153 offset:3072
	s_add_u32 s28, s2, 0xfffc0080
	s_addc_u32 s29, s3, -1
	s_cmp_eq_u32 s58, 12
	s_cselect_b32 s31, s23, s29
	s_cselect_b32 s30, s54, s28
	s_cselect_b32 s29, s21, s57
	s_cselect_b32 s28, s55, s56
	v_lshl_add_u64 v[148:149], s[2:3], 0, v[136:137]
	s_add_i32 m0, s37, 0xc000
	ds_read_b128 v[170:173], v154
	ds_read_b128 v[176:179], v154 offset:1024
	ds_read_b128 v[180:183], v154 offset:2048
	ds_read_b128 v[184:187], v154 offset:3072
	ds_read_b128 v[188:191], v154 offset:4096
	ds_read_b128 v[192:195], v154 offset:5120
	ds_read_b128 v[196:199], v154 offset:6144
	ds_read_b128 v[200:203], v154 offset:7168
	global_load_lds_dwordx4 v[148:149], off
	v_lshl_add_u64 v[148:149], s[2:3], 0, v[138:139]
	s_add_i32 m0, s37, 0xe000
	s_nop 0
	global_load_lds_dwordx4 v[148:149], off
	s_waitcnt lgkmcnt(8)
	s_barrier
	s_waitcnt lgkmcnt(0)
	s_setprio 1
	s_waitcnt lgkmcnt(0)
	v_mfma_f32_16x16x32_bf16 v[124:127], v[144:147], v[170:173], v[124:127]
	v_mfma_f32_16x16x32_bf16 v[120:123], v[162:165], v[170:173], v[120:123]
	v_mfma_f32_16x16x32_bf16 v[116:119], v[144:147], v[180:183], v[116:119]
	v_mfma_f32_16x16x32_bf16 v[112:115], v[162:165], v[180:183], v[112:115]
	v_mfma_f32_16x16x32_bf16 v[104:107], v[144:147], v[188:191], v[104:107]
	v_mfma_f32_16x16x32_bf16 v[96:99], v[162:165], v[188:191], v[96:99]
	v_mfma_f32_16x16x32_bf16 v[76:79], v[144:147], v[196:199], v[76:79]
	v_mfma_f32_16x16x32_bf16 v[72:75], v[162:165], v[196:199], v[72:75]
	v_mfma_f32_16x16x32_bf16 v[124:127], v[158:161], v[176:179], v[124:127]
	v_mfma_f32_16x16x32_bf16 v[120:123], v[166:169], v[176:179], v[120:123]
	v_mfma_f32_16x16x32_bf16 v[116:119], v[158:161], v[184:187], v[116:119]
	v_mfma_f32_16x16x32_bf16 v[112:115], v[166:169], v[184:187], v[112:115]
	v_mfma_f32_16x16x32_bf16 v[104:107], v[158:161], v[192:195], v[104:107]
	v_mfma_f32_16x16x32_bf16 v[96:99], v[166:169], v[192:195], v[96:99]
	v_mfma_f32_16x16x32_bf16 v[76:79], v[158:161], v[200:203], v[76:79]
	v_mfma_f32_16x16x32_bf16 v[72:75], v[166:169], v[200:203], v[72:75]
	s_setprio 0
	s_barrier
	s_add_i32 s59, s50, s34
	v_lshl_add_u64 v[148:149], s[28:29], 0, v[132:133]
	s_mov_b32 m0, s59
	ds_read_b128 v[204:207], v155
	ds_read_b128 v[212:215], v155 offset:1024
	ds_read_b128 v[216:219], v155 offset:2048
	ds_read_b128 v[220:223], v155 offset:3072
	global_load_lds_dwordx4 v[148:149], off
	v_lshl_add_u64 v[208:209], s[28:29], 0, v[128:129]
	s_add_i32 m0, s59, 0x2000
	s_nop 0
	global_load_lds_dwordx4 v[208:209], off
	s_barrier
	s_waitcnt lgkmcnt(0)
	s_setprio 1
	s_waitcnt lgkmcnt(0)
	v_mfma_f32_16x16x32_bf16 v[108:111], v[204:207], v[170:173], v[108:111]
	v_mfma_f32_16x16x32_bf16 v[100:103], v[216:219], v[170:173], v[100:103]
	v_mfma_f32_16x16x32_bf16 v[92:95], v[204:207], v[180:183], v[92:95]
	v_mfma_f32_16x16x32_bf16 v[88:91], v[216:219], v[180:183], v[88:91]
	v_mfma_f32_16x16x32_bf16 v[84:87], v[204:207], v[188:191], v[84:87]
	v_mfma_f32_16x16x32_bf16 v[80:83], v[216:219], v[188:191], v[80:83]
	v_mfma_f32_16x16x32_bf16 v[68:71], v[204:207], v[196:199], v[68:71]
	v_mfma_f32_16x16x32_bf16 v[64:67], v[216:219], v[196:199], v[64:67]
	v_mfma_f32_16x16x32_bf16 v[108:111], v[212:215], v[176:179], v[108:111]
	v_mfma_f32_16x16x32_bf16 v[100:103], v[220:223], v[176:179], v[100:103]
	v_mfma_f32_16x16x32_bf16 v[92:95], v[212:215], v[184:187], v[92:95]
	v_mfma_f32_16x16x32_bf16 v[88:91], v[220:223], v[184:187], v[88:91]
	v_mfma_f32_16x16x32_bf16 v[84:87], v[212:215], v[192:195], v[84:87]
	v_mfma_f32_16x16x32_bf16 v[80:83], v[220:223], v[192:195], v[80:83]
	v_mfma_f32_16x16x32_bf16 v[68:71], v[212:215], v[200:203], v[68:71]
	v_mfma_f32_16x16x32_bf16 v[64:67], v[220:223], v[200:203], v[64:67]
	s_setprio 0
	s_mov_b32 m0, s37
	v_lshl_add_u64 v[224:225], s[30:31], 0, v[134:135]
	s_barrier
	ds_read_b128 v[170:173], v154 offset:16384
	ds_read_b128 v[176:179], v154 offset:17408
	ds_read_b128 v[180:183], v154 offset:18432
	ds_read_b128 v[184:187], v154 offset:19456
	ds_read_b128 v[188:191], v154 offset:20480
	ds_read_b128 v[192:195], v154 offset:21504
	ds_read_b128 v[196:199], v154 offset:22528
	ds_read_b128 v[200:203], v154 offset:23552
	global_load_lds_dwordx4 v[224:225], off
	v_lshl_add_u64 v[226:227], s[30:31], 0, v[130:131]
	s_mov_b32 m0, s38
	s_nop 0
	global_load_lds_dwordx4 v[226:227], off
	s_barrier
	s_waitcnt lgkmcnt(0)
	s_setprio 1
	s_waitcnt lgkmcnt(0)
	v_mfma_f32_16x16x32_bf16 v[60:63], v[144:147], v[170:173], v[60:63]
	v_mfma_f32_16x16x32_bf16 v[56:59], v[162:165], v[170:173], v[56:59]
	v_mfma_f32_16x16x32_bf16 v[44:47], v[144:147], v[180:183], v[44:47]
	v_mfma_f32_16x16x32_bf16 v[40:43], v[162:165], v[180:183], v[40:43]
	v_mfma_f32_16x16x32_bf16 v[28:31], v[144:147], v[188:191], v[28:31]
	v_mfma_f32_16x16x32_bf16 v[24:27], v[162:165], v[188:191], v[24:27]
	v_mfma_f32_16x16x32_bf16 v[12:15], v[144:147], v[196:199], v[12:15]
	v_mfma_f32_16x16x32_bf16 v[8:11], v[162:165], v[196:199], v[8:11]
	v_mfma_f32_16x16x32_bf16 v[60:63], v[158:161], v[176:179], v[60:63]
	v_mfma_f32_16x16x32_bf16 v[56:59], v[166:169], v[176:179], v[56:59]
	v_mfma_f32_16x16x32_bf16 v[44:47], v[158:161], v[184:187], v[44:47]
	v_mfma_f32_16x16x32_bf16 v[40:43], v[166:169], v[184:187], v[40:43]
	v_mfma_f32_16x16x32_bf16 v[28:31], v[158:161], v[192:195], v[28:31]
	v_mfma_f32_16x16x32_bf16 v[24:27], v[166:169], v[192:195], v[24:27]
	v_mfma_f32_16x16x32_bf16 v[12:15], v[158:161], v[200:203], v[12:15]
	v_mfma_f32_16x16x32_bf16 v[8:11], v[166:169], v[200:203], v[8:11]
	s_setprio 0
	s_barrier
	s_add_u32 s60, s28, 0x40000
	s_addc_u32 s61, s29, 0
	s_add_i32 s59, s51, s34
	v_lshl_add_u64 v[144:145], s[60:61], 0, v[132:133]
	s_mov_b32 m0, s59
	s_nop 0
	global_load_lds_dwordx4 v[144:145], off
	v_lshl_add_u64 v[144:145], s[60:61], 0, v[128:129]
	s_add_i32 m0, s59, 0x2000
	s_nop 0
	global_load_lds_dwordx4 v[144:145], off
	s_waitcnt vmcnt(6)
	s_barrier
	s_setprio 1
	v_mfma_f32_16x16x32_bf16 v[52:55], v[204:207], v[170:173], v[52:55]
	v_mfma_f32_16x16x32_bf16 v[48:51], v[216:219], v[170:173], v[48:51]
	v_mfma_f32_16x16x32_bf16 v[36:39], v[204:207], v[180:183], v[36:39]
	v_mfma_f32_16x16x32_bf16 v[32:35], v[216:219], v[180:183], v[32:35]
	v_mfma_f32_16x16x32_bf16 v[20:23], v[204:207], v[188:191], v[20:23]
	v_mfma_f32_16x16x32_bf16 v[16:19], v[216:219], v[188:191], v[16:19]
	v_mfma_f32_16x16x32_bf16 v[4:7], v[204:207], v[196:199], v[4:7]
	v_mfma_f32_16x16x32_bf16 v[0:3], v[216:219], v[196:199], v[0:3]
	v_mfma_f32_16x16x32_bf16 v[52:55], v[212:215], v[176:179], v[52:55]
	v_mfma_f32_16x16x32_bf16 v[48:51], v[220:223], v[176:179], v[48:51]
	v_mfma_f32_16x16x32_bf16 v[36:39], v[212:215], v[184:187], v[36:39]
	v_mfma_f32_16x16x32_bf16 v[32:35], v[220:223], v[184:187], v[32:35]
	v_mfma_f32_16x16x32_bf16 v[20:23], v[212:215], v[192:195], v[20:23]
	v_mfma_f32_16x16x32_bf16 v[16:19], v[220:223], v[192:195], v[16:19]
	v_mfma_f32_16x16x32_bf16 v[4:7], v[212:215], v[200:203], v[4:7]
	v_mfma_f32_16x16x32_bf16 v[0:3], v[220:223], v[200:203], v[0:3]
	s_setprio 0
	s_add_i32 s59, 0, 0x18000
	v_add_u32_e32 v157, s59, v151
	s_barrier
	ds_read_b128 v[144:147], v157
	ds_read_b128 v[158:161], v157 offset:1024
	ds_read_b128 v[162:165], v157 offset:2048
	ds_read_b128 v[166:169], v157 offset:3072
	s_add_u32 s30, s30, 0x40000
	s_addc_u32 s31, s31, 0
	s_mov_b32 m0, s39
	v_lshl_add_u64 v[204:205], s[30:31], 0, v[134:135]
	ds_read_b128 v[170:173], v154 offset:32768
	ds_read_b128 v[176:179], v154 offset:33792
	ds_read_b128 v[180:183], v154 offset:34816
	ds_read_b128 v[184:187], v154 offset:35840
	ds_read_b128 v[188:191], v154 offset:36864
	ds_read_b128 v[192:195], v154 offset:37888
	ds_read_b128 v[196:199], v154 offset:38912
	ds_read_b128 v[200:203], v154 offset:39936
	global_load_lds_dwordx4 v[204:205], off
	v_lshl_add_u64 v[204:205], s[30:31], 0, v[130:131]
	s_mov_b32 m0, s40
	s_nop 0
	global_load_lds_dwordx4 v[204:205], off
	s_waitcnt lgkmcnt(8)
	s_barrier
	s_waitcnt lgkmcnt(0)
	s_setprio 1
	s_waitcnt lgkmcnt(0)
	v_mfma_f32_16x16x32_bf16 v[124:127], v[144:147], v[170:173], v[124:127]
	v_mfma_f32_16x16x32_bf16 v[120:123], v[162:165], v[170:173], v[120:123]
	v_mfma_f32_16x16x32_bf16 v[116:119], v[144:147], v[180:183], v[116:119]
	v_mfma_f32_16x16x32_bf16 v[112:115], v[162:165], v[180:183], v[112:115]
	v_mfma_f32_16x16x32_bf16 v[104:107], v[144:147], v[188:191], v[104:107]
	v_mfma_f32_16x16x32_bf16 v[96:99], v[162:165], v[188:191], v[96:99]
	v_mfma_f32_16x16x32_bf16 v[76:79], v[144:147], v[196:199], v[76:79]
	v_mfma_f32_16x16x32_bf16 v[72:75], v[162:165], v[196:199], v[72:75]
	v_mfma_f32_16x16x32_bf16 v[124:127], v[158:161], v[176:179], v[124:127]
	v_mfma_f32_16x16x32_bf16 v[120:123], v[166:169], v[176:179], v[120:123]
	v_mfma_f32_16x16x32_bf16 v[116:119], v[158:161], v[184:187], v[116:119]
	v_mfma_f32_16x16x32_bf16 v[112:115], v[166:169], v[184:187], v[112:115]
	v_mfma_f32_16x16x32_bf16 v[104:107], v[158:161], v[192:195], v[104:107]
	v_mfma_f32_16x16x32_bf16 v[96:99], v[166:169], v[192:195], v[96:99]
	v_mfma_f32_16x16x32_bf16 v[76:79], v[158:161], v[200:203], v[76:79]
	v_mfma_f32_16x16x32_bf16 v[72:75], v[166:169], v[200:203], v[72:75]
	s_setprio 0
	s_barrier
	s_add_i32 s30, 0, 0x1c000
	s_add_i32 s31, s59, s34
	v_add_u32_e32 v157, s30, v151
	v_lshl_add_u64 v[148:149], v[148:149], 0, s[8:9]
	s_mov_b32 m0, s31
	ds_read_b128 v[204:207], v157
	ds_read_b128 v[212:215], v157 offset:1024
	ds_read_b128 v[216:219], v157 offset:2048
	ds_read_b128 v[220:223], v157 offset:3072
	global_load_lds_dwordx4 v[148:149], off
	v_lshl_add_u64 v[148:149], v[208:209], 0, s[8:9]
	s_add_i32 m0, s31, 0x2000
	s_nop 0
	global_load_lds_dwordx4 v[148:149], off
	s_barrier
	s_waitcnt lgkmcnt(0)
	s_setprio 1
	s_waitcnt lgkmcnt(0)
	v_mfma_f32_16x16x32_bf16 v[108:111], v[204:207], v[170:173], v[108:111]
	v_mfma_f32_16x16x32_bf16 v[100:103], v[216:219], v[170:173], v[100:103]
	v_mfma_f32_16x16x32_bf16 v[92:95], v[204:207], v[180:183], v[92:95]
	v_mfma_f32_16x16x32_bf16 v[88:91], v[216:219], v[180:183], v[88:91]
	v_mfma_f32_16x16x32_bf16 v[84:87], v[204:207], v[188:191], v[84:87]
	v_mfma_f32_16x16x32_bf16 v[80:83], v[216:219], v[188:191], v[80:83]
	v_mfma_f32_16x16x32_bf16 v[68:71], v[204:207], v[196:199], v[68:71]
	v_mfma_f32_16x16x32_bf16 v[64:67], v[216:219], v[196:199], v[64:67]
	v_mfma_f32_16x16x32_bf16 v[108:111], v[212:215], v[176:179], v[108:111]
	v_mfma_f32_16x16x32_bf16 v[100:103], v[220:223], v[176:179], v[100:103]
	v_mfma_f32_16x16x32_bf16 v[92:95], v[212:215], v[184:187], v[92:95]
	v_mfma_f32_16x16x32_bf16 v[88:91], v[220:223], v[184:187], v[88:91]
	v_mfma_f32_16x16x32_bf16 v[84:87], v[212:215], v[192:195], v[84:87]
	v_mfma_f32_16x16x32_bf16 v[80:83], v[220:223], v[192:195], v[80:83]
	v_mfma_f32_16x16x32_bf16 v[68:71], v[212:215], v[200:203], v[68:71]
	v_mfma_f32_16x16x32_bf16 v[64:67], v[220:223], v[200:203], v[64:67]
	s_setprio 0
	s_mov_b32 m0, s42
	v_lshl_add_u64 v[148:149], v[224:225], 0, s[8:9]
	s_barrier
	ds_read_b128 v[170:173], v154 offset:49152
	ds_read_b128 v[176:179], v154 offset:50176
	ds_read_b128 v[180:183], v154 offset:51200
	ds_read_b128 v[184:187], v154 offset:52224
	ds_read_b128 v[188:191], v154 offset:53248
	ds_read_b128 v[192:195], v154 offset:54272
	ds_read_b128 v[196:199], v154 offset:55296
	ds_read_b128 v[200:203], v154 offset:56320
	global_load_lds_dwordx4 v[148:149], off
	v_lshl_add_u64 v[148:149], v[226:227], 0, s[8:9]
	s_mov_b32 m0, s43
	s_nop 0
	global_load_lds_dwordx4 v[148:149], off
	s_barrier
	s_waitcnt lgkmcnt(0)
	s_setprio 1
	s_waitcnt lgkmcnt(0)
	v_mfma_f32_16x16x32_bf16 v[60:63], v[144:147], v[170:173], v[60:63]
	v_mfma_f32_16x16x32_bf16 v[56:59], v[162:165], v[170:173], v[56:59]
	v_mfma_f32_16x16x32_bf16 v[44:47], v[144:147], v[180:183], v[44:47]
	v_mfma_f32_16x16x32_bf16 v[40:43], v[162:165], v[180:183], v[40:43]
	v_mfma_f32_16x16x32_bf16 v[28:31], v[144:147], v[188:191], v[28:31]
	v_mfma_f32_16x16x32_bf16 v[24:27], v[162:165], v[188:191], v[24:27]
	v_mfma_f32_16x16x32_bf16 v[12:15], v[144:147], v[196:199], v[12:15]
	v_mfma_f32_16x16x32_bf16 v[8:11], v[162:165], v[196:199], v[8:11]
	v_mfma_f32_16x16x32_bf16 v[60:63], v[158:161], v[176:179], v[60:63]
	v_mfma_f32_16x16x32_bf16 v[56:59], v[166:169], v[176:179], v[56:59]
	v_mfma_f32_16x16x32_bf16 v[44:47], v[158:161], v[184:187], v[44:47]
	v_mfma_f32_16x16x32_bf16 v[40:43], v[166:169], v[184:187], v[40:43]
	v_mfma_f32_16x16x32_bf16 v[28:31], v[158:161], v[192:195], v[28:31]
	v_mfma_f32_16x16x32_bf16 v[24:27], v[166:169], v[192:195], v[24:27]
	v_mfma_f32_16x16x32_bf16 v[12:15], v[158:161], v[200:203], v[12:15]
	v_mfma_f32_16x16x32_bf16 v[8:11], v[166:169], v[200:203], v[8:11]
	s_setprio 0
	s_barrier
	s_add_u32 s28, s28, 0x40080
	s_addc_u32 s29, s29, 0
	s_add_i32 s30, s30, s34
	v_lshl_add_u64 v[144:145], s[28:29], 0, v[132:133]
	s_mov_b32 m0, s30
	s_nop 0
	global_load_lds_dwordx4 v[144:145], off
	v_lshl_add_u64 v[144:145], s[28:29], 0, v[128:129]
	s_add_i32 m0, s30, 0x2000
	s_nop 0
	global_load_lds_dwordx4 v[144:145], off
	s_waitcnt vmcnt(6)
	s_barrier
	s_setprio 1
	v_mfma_f32_16x16x32_bf16 v[52:55], v[204:207], v[170:173], v[52:55]
	v_mfma_f32_16x16x32_bf16 v[48:51], v[216:219], v[170:173], v[48:51]
	v_mfma_f32_16x16x32_bf16 v[36:39], v[204:207], v[180:183], v[36:39]
	v_mfma_f32_16x16x32_bf16 v[32:35], v[216:219], v[180:183], v[32:35]
	v_mfma_f32_16x16x32_bf16 v[20:23], v[204:207], v[188:191], v[20:23]
	v_mfma_f32_16x16x32_bf16 v[16:19], v[216:219], v[188:191], v[16:19]
	v_mfma_f32_16x16x32_bf16 v[4:7], v[204:207], v[196:199], v[4:7]
	v_mfma_f32_16x16x32_bf16 v[0:3], v[216:219], v[196:199], v[0:3]
	v_mfma_f32_16x16x32_bf16 v[52:55], v[212:215], v[176:179], v[52:55]
	v_mfma_f32_16x16x32_bf16 v[48:51], v[220:223], v[176:179], v[48:51]
	v_mfma_f32_16x16x32_bf16 v[36:39], v[212:215], v[184:187], v[36:39]
	v_mfma_f32_16x16x32_bf16 v[32:35], v[220:223], v[184:187], v[32:35]
	v_mfma_f32_16x16x32_bf16 v[20:23], v[212:215], v[192:195], v[20:23]
	v_mfma_f32_16x16x32_bf16 v[16:19], v[220:223], v[192:195], v[16:19]
	v_mfma_f32_16x16x32_bf16 v[4:7], v[212:215], v[200:203], v[4:7]
	v_mfma_f32_16x16x32_bf16 v[0:3], v[220:223], v[200:203], v[0:3]
	s_setprio 0
	s_add_i32 s58, s58, 2
	s_add_u32 s2, s2, 0x100
	s_addc_u32 s3, s3, 0
	s_add_u32 s56, s56, 0x100
	s_addc_u32 s57, s57, 0
	s_cmp_gt_u32 s58, 13
	s_barrier
	s_cbranch_scc0 .LBB0_946
	v_lshl_add_u32 v144, s0, 8, v150
	v_ashrrev_i32_e32 v145, 31, v144
	v_lshl_add_u64 v[146:147], v[144:145], 2, s[18:19]
	global_load_dword v145, v[146:147], off
	global_load_dword v157, v[146:147], off offset:64
	global_load_dword v164, v[146:147], off offset:128
	global_load_dword v165, v[146:147], off offset:192
	global_load_dword v166, v[146:147], off offset:512
	global_load_dword v167, v[146:147], off offset:576
	global_load_dword v168, v[146:147], off offset:640
	global_load_dword v169, v[146:147], off offset:704
	v_mov_b64_e32 v[146:147], s[92:93]
	v_or_b32_e32 v160, 16, v144
	v_or_b32_e32 v162, 32, v144
	v_lshl_or_b32 v148, s1, 8, v152
	v_mad_i64_i32 v[158:159], s[0:1], v144, s52, v[146:147]
	v_mad_i64_i32 v[160:161], s[0:1], v160, s52, v[146:147]
	v_mad_i64_i32 v[162:163], s[0:1], v162, s52, v[146:147]
	v_ashrrev_i32_e32 v149, 31, v148
	v_lshlrev_b64 v[148:149], 1, v[148:149]
	v_lshl_add_u64 v[158:159], v[158:159], 0, v[148:149]
	v_lshl_add_u64 v[160:161], v[160:161], 0, v[148:149]
	v_lshl_add_u64 v[162:163], v[162:163], 0, v[148:149]
	v_add_u32_e32 v170, 0x80, v144
	s_mov_b64 s[28:29], s[26:27]
	s_waitcnt vmcnt(0)
	v_fmamk_f32 v145, v145, 0x3a800000, v156
	v_fmamk_f32 v157, v157, 0x3a800000, v156
	v_fmamk_f32 v164, v164, 0x3a800000, v156
	v_fmamk_f32 v171, v165, 0x3a800000, v156
	v_fmamk_f32 v172, v166, 0x3a800000, v156
	v_mul_f32_e32 v165, 0x4b800000, v145
	v_mul_f32_e32 v166, 0x4b800000, v157
	v_cmp_gt_f32_e32 vcc, s53, v145
	v_cmp_gt_f32_e64 s[0:1], s53, v157
	v_fmamk_f32 v173, v167, 0x3a800000, v156
	v_mul_f32_e32 v167, 0x4b800000, v164
	v_cndmask_b32_e32 v145, v145, v165, vcc
	v_cndmask_b32_e64 v157, v157, v166, s[0:1]
	v_cmp_gt_f32_e64 s[2:3], s53, v164
	v_rsq_f32_e32 v145, v145
	v_rsq_f32_e32 v157, v157
	v_cndmask_b32_e64 v164, v164, v167, s[2:3]
	v_rsq_f32_e32 v165, v164
	v_mul_f32_e32 v164, 0x45800000, v145
	v_mul_f32_e32 v166, 0x45800000, v157
	v_cndmask_b32_e32 v164, v145, v164, vcc
	v_mul_f32_e32 v167, 0x45800000, v165
	v_cndmask_b32_e64 v166, v157, v166, s[0:1]
	v_fmamk_f32 v175, v168, 0x3a800000, v156
	v_cndmask_b32_e64 v168, v165, v167, s[2:3]
	v_pk_mul_f32 v[126:127], v[126:127], v[164:165] op_sel_hi:[1,0]
	v_pk_mul_f32 v[124:125], v[124:125], v[164:165] op_sel_hi:[1,0]
	v_pk_mul_f32 v[122:123], v[122:123], v[164:165] op_sel_hi:[1,0]
	v_pk_mul_f32 v[120:121], v[120:121], v[164:165] op_sel_hi:[1,0]
	v_pk_mul_f32 v[110:111], v[110:111], v[164:165] op_sel_hi:[1,0]
	v_pk_mul_f32 v[108:109], v[108:109], v[164:165] op_sel_hi:[1,0]
	v_pk_mul_f32 v[102:103], v[102:103], v[164:165] op_sel_hi:[1,0]
	v_pk_mul_f32 v[100:101], v[100:101], v[164:165] op_sel_hi:[1,0]
	v_pk_mul_f32 v[118:119], v[118:119], v[166:167] op_sel_hi:[1,0]
	v_pk_mul_f32 v[116:117], v[116:117], v[166:167] op_sel_hi:[1,0]
	v_pk_mul_f32 v[114:115], v[114:115], v[166:167] op_sel_hi:[1,0]
	v_pk_mul_f32 v[112:113], v[112:113], v[166:167] op_sel_hi:[1,0]
	v_pk_mul_f32 v[94:95], v[94:95], v[166:167] op_sel_hi:[1,0]
	v_pk_mul_f32 v[92:93], v[92:93], v[166:167] op_sel_hi:[1,0]
	v_pk_mul_f32 v[164:165], v[90:91], v[166:167] op_sel_hi:[1,0]
	v_pk_mul_f32 v[166:167], v[88:89], v[166:167] op_sel_hi:[1,0]
	v_cvt_pk_bf16_f32 v88, v124, v125
	v_cvt_pk_bf16_f32 v89, v126, v127
	v_cvt_pk_bf16_f32 v90, v120, v121
	v_cvt_pk_bf16_f32 v91, v122, v123
	global_store_dwordx4 v[158:159], v[88:91], off nt
	v_fmamk_f32 v169, v169, 0x3a800000, v156
	v_pk_mul_f32 v[106:107], v[106:107], v[168:169] op_sel_hi:[1,0]
	v_cvt_pk_bf16_f32 v88, v108, v109
	v_cvt_pk_bf16_f32 v89, v110, v111
	v_cvt_pk_bf16_f32 v90, v100, v101
	v_cvt_pk_bf16_f32 v91, v102, v103
	global_store_dwordx4 v[158:159], v[88:91], off offset:256 nt
	v_pk_mul_f32 v[104:105], v[104:105], v[168:169] op_sel_hi:[1,0]
	v_pk_mul_f32 v[98:99], v[98:99], v[168:169] op_sel_hi:[1,0]
	v_cvt_pk_bf16_f32 v88, v116, v117
	v_cvt_pk_bf16_f32 v89, v118, v119
	v_cvt_pk_bf16_f32 v90, v112, v113
	v_cvt_pk_bf16_f32 v91, v114, v115
	global_store_dwordx4 v[160:161], v[88:91], off nt
	v_pk_mul_f32 v[96:97], v[96:97], v[168:169] op_sel_hi:[1,0]
	v_pk_mul_f32 v[86:87], v[86:87], v[168:169] op_sel_hi:[1,0]
	v_cvt_pk_bf16_f32 v88, v92, v93
	v_cvt_pk_bf16_f32 v89, v94, v95
	v_cvt_pk_bf16_f32 v90, v166, v167
	v_cvt_pk_bf16_f32 v91, v164, v165
	global_store_dwordx4 v[160:161], v[88:91], off offset:256 nt
	v_pk_mul_f32 v[84:85], v[84:85], v[168:169] op_sel_hi:[1,0]
	v_cmp_gt_f32_e32 vcc, s53, v171
	v_cvt_pk_bf16_f32 v88, v104, v105
	v_cvt_pk_bf16_f32 v89, v106, v107
	v_cvt_pk_bf16_f32 v90, v96, v97
	v_cvt_pk_bf16_f32 v91, v98, v99
	global_store_dwordx4 v[162:163], v[88:91], off nt
	s_mov_b64 s[2:3], s[24:25]
	s_nop 0
	v_pk_mul_f32 v[88:89], v[82:83], v[168:169] op_sel_hi:[1,0]
	v_pk_mul_f32 v[82:83], v[80:81], v[168:169] op_sel_hi:[1,0]
	v_cvt_pk_bf16_f32 v80, v84, v85
	v_cvt_pk_bf16_f32 v81, v86, v87
	s_nop 0
	v_cvt_pk_bf16_f32 v82, v82, v83
	v_cvt_pk_bf16_f32 v83, v88, v89
	global_store_dwordx4 v[162:163], v[80:83], off offset:256 nt
	s_nop 1
	v_mul_f32_e32 v81, 0x4b800000, v171
	v_cndmask_b32_e32 v81, v171, v81, vcc
	v_rsq_f32_e32 v82, v81
	v_or_b32_e32 v80, 48, v144
	v_mad_i64_i32 v[80:81], s[0:1], v80, s52, v[146:147]
	v_mul_f32_e32 v83, 0x45800000, v82
	v_cndmask_b32_e32 v82, v82, v83, vcc
	v_lshl_add_u64 v[80:81], v[80:81], 0, v[148:149]
	v_pk_mul_f32 v[78:79], v[78:79], v[82:83] op_sel_hi:[1,0]
	v_pk_mul_f32 v[76:77], v[76:77], v[82:83] op_sel_hi:[1,0]
	v_pk_mul_f32 v[84:85], v[74:75], v[82:83] op_sel_hi:[1,0]
	v_pk_mul_f32 v[74:75], v[72:73], v[82:83] op_sel_hi:[1,0]
	v_cvt_pk_bf16_f32 v72, v76, v77
	v_cvt_pk_bf16_f32 v73, v78, v79
	v_pk_mul_f32 v[68:69], v[68:69], v[82:83] op_sel_hi:[1,0]
	v_cvt_pk_bf16_f32 v74, v74, v75
	v_cvt_pk_bf16_f32 v75, v84, v85
	global_store_dwordx4 v[80:81], v[72:75], off nt
	v_pk_mul_f32 v[70:71], v[70:71], v[82:83] op_sel_hi:[1,0]
	v_cmp_gt_f32_e32 vcc, s53, v172
	v_pk_mul_f32 v[72:73], v[66:67], v[82:83] op_sel_hi:[1,0]
	v_pk_mul_f32 v[66:67], v[64:65], v[82:83] op_sel_hi:[1,0]
	v_cvt_pk_bf16_f32 v64, v68, v69
	v_cvt_pk_bf16_f32 v65, v70, v71
	s_nop 0
	v_cvt_pk_bf16_f32 v66, v66, v67
	v_cvt_pk_bf16_f32 v67, v72, v73
	global_store_dwordx4 v[80:81], v[64:67], off offset:256 nt
	s_nop 1
	v_mul_f32_e32 v64, 0x4b800000, v172
	v_cndmask_b32_e32 v64, v172, v64, vcc
	v_rsq_f32_e32 v66, v64
	v_mad_i64_i32 v[64:65], s[0:1], v170, s52, v[146:147]
	v_lshl_add_u64 v[64:65], v[64:65], 0, v[148:149]
	v_mul_f32_e32 v67, 0x45800000, v66
	v_cndmask_b32_e32 v66, v66, v67, vcc
	v_pk_mul_f32 v[62:63], v[62:63], v[66:67] op_sel_hi:[1,0]
	v_pk_mul_f32 v[60:61], v[60:61], v[66:67] op_sel_hi:[1,0]
	v_pk_mul_f32 v[68:69], v[58:59], v[66:67] op_sel_hi:[1,0]
	v_pk_mul_f32 v[58:59], v[56:57], v[66:67] op_sel_hi:[1,0]
	v_cvt_pk_bf16_f32 v56, v60, v61
	v_cvt_pk_bf16_f32 v57, v62, v63
	v_pk_mul_f32 v[54:55], v[54:55], v[66:67] op_sel_hi:[1,0]
	v_cvt_pk_bf16_f32 v58, v58, v59
	v_cvt_pk_bf16_f32 v59, v68, v69
	global_store_dwordx4 v[64:65], v[56:59], off nt
	v_pk_mul_f32 v[52:53], v[52:53], v[66:67] op_sel_hi:[1,0]
	v_cmp_gt_f32_e32 vcc, s53, v173
	v_pk_mul_f32 v[56:57], v[50:51], v[66:67] op_sel_hi:[1,0]
	v_pk_mul_f32 v[50:51], v[48:49], v[66:67] op_sel_hi:[1,0]
	v_cvt_pk_bf16_f32 v48, v52, v53
	v_cvt_pk_bf16_f32 v49, v54, v55
	s_nop 0
	v_cvt_pk_bf16_f32 v50, v50, v51
	v_cvt_pk_bf16_f32 v51, v56, v57
	global_store_dwordx4 v[64:65], v[48:51], off offset:256 nt
	s_nop 1
	v_mul_f32_e32 v49, 0x4b800000, v173
	v_cndmask_b32_e32 v49, v173, v49, vcc
	v_rsq_f32_e32 v50, v49
	v_add_u32_e32 v48, 0x90, v144
	v_mad_i64_i32 v[48:49], s[0:1], v48, s52, v[146:147]
	v_mul_f32_e32 v51, 0x45800000, v50
	v_cndmask_b32_e32 v50, v50, v51, vcc
	v_lshl_add_u64 v[48:49], v[48:49], 0, v[148:149]
	v_pk_mul_f32 v[46:47], v[46:47], v[50:51] op_sel_hi:[1,0]
	v_pk_mul_f32 v[44:45], v[44:45], v[50:51] op_sel_hi:[1,0]
	v_pk_mul_f32 v[52:53], v[42:43], v[50:51] op_sel_hi:[1,0]
	v_pk_mul_f32 v[42:43], v[40:41], v[50:51] op_sel_hi:[1,0]
	v_cvt_pk_bf16_f32 v40, v44, v45
	v_cvt_pk_bf16_f32 v41, v46, v47
	v_pk_mul_f32 v[38:39], v[38:39], v[50:51] op_sel_hi:[1,0]
	v_cvt_pk_bf16_f32 v42, v42, v43
	v_cvt_pk_bf16_f32 v43, v52, v53
	global_store_dwordx4 v[48:49], v[40:43], off nt
	v_pk_mul_f32 v[36:37], v[36:37], v[50:51] op_sel_hi:[1,0]
	v_cmp_gt_f32_e32 vcc, s53, v175
	v_pk_mul_f32 v[40:41], v[34:35], v[50:51] op_sel_hi:[1,0]
	v_pk_mul_f32 v[34:35], v[32:33], v[50:51] op_sel_hi:[1,0]
	v_cvt_pk_bf16_f32 v32, v36, v37
	v_cvt_pk_bf16_f32 v33, v38, v39
	s_nop 0
	v_cvt_pk_bf16_f32 v34, v34, v35
	v_cvt_pk_bf16_f32 v35, v40, v41
	global_store_dwordx4 v[48:49], v[32:35], off offset:256 nt
	s_nop 1
	v_mul_f32_e32 v33, 0x4b800000, v175
	v_cndmask_b32_e32 v33, v175, v33, vcc
	v_rsq_f32_e32 v34, v33
	v_add_u32_e32 v32, 0xa0, v144
	v_mad_i64_i32 v[32:33], s[0:1], v32, s52, v[146:147]
	v_mul_f32_e32 v35, 0x45800000, v34
	v_cndmask_b32_e32 v34, v34, v35, vcc
	v_lshl_add_u64 v[32:33], v[32:33], 0, v[148:149]
	v_pk_mul_f32 v[30:31], v[30:31], v[34:35] op_sel_hi:[1,0]
	v_pk_mul_f32 v[28:29], v[28:29], v[34:35] op_sel_hi:[1,0]
	v_pk_mul_f32 v[36:37], v[26:27], v[34:35] op_sel_hi:[1,0]
	v_pk_mul_f32 v[26:27], v[24:25], v[34:35] op_sel_hi:[1,0]
	v_cvt_pk_bf16_f32 v24, v28, v29
	v_cvt_pk_bf16_f32 v25, v30, v31
	v_pk_mul_f32 v[22:23], v[22:23], v[34:35] op_sel_hi:[1,0]
	v_cvt_pk_bf16_f32 v26, v26, v27
	v_cvt_pk_bf16_f32 v27, v36, v37
	global_store_dwordx4 v[32:33], v[24:27], off nt
	v_pk_mul_f32 v[20:21], v[20:21], v[34:35] op_sel_hi:[1,0]
	v_cmp_gt_f32_e32 vcc, s53, v169
	v_pk_mul_f32 v[24:25], v[18:19], v[34:35] op_sel_hi:[1,0]
	v_pk_mul_f32 v[18:19], v[16:17], v[34:35] op_sel_hi:[1,0]
	v_cvt_pk_bf16_f32 v16, v20, v21
	v_cvt_pk_bf16_f32 v17, v22, v23
	s_nop 0
	v_cvt_pk_bf16_f32 v18, v18, v19
	v_cvt_pk_bf16_f32 v19, v24, v25
	global_store_dwordx4 v[32:33], v[16:19], off offset:256 nt
	s_nop 1
	v_mul_f32_e32 v17, 0x4b800000, v169
	v_cndmask_b32_e32 v17, v169, v17, vcc
	v_rsq_f32_e32 v18, v17
	v_add_u32_e32 v16, 0xb0, v144
	v_mad_i64_i32 v[16:17], s[0:1], v16, s52, v[146:147]
	v_mul_f32_e32 v19, 0x45800000, v18
	v_cndmask_b32_e32 v18, v18, v19, vcc
	v_lshl_add_u64 v[16:17], v[16:17], 0, v[148:149]
	v_pk_mul_f32 v[14:15], v[14:15], v[18:19] op_sel_hi:[1,0]
	v_pk_mul_f32 v[12:13], v[12:13], v[18:19] op_sel_hi:[1,0]
	v_pk_mul_f32 v[20:21], v[10:11], v[18:19] op_sel_hi:[1,0]
	v_pk_mul_f32 v[10:11], v[8:9], v[18:19] op_sel_hi:[1,0]
	v_cvt_pk_bf16_f32 v8, v12, v13
	v_cvt_pk_bf16_f32 v9, v14, v15
	s_and_b64 vcc, exec, s[6:7]
	v_cvt_pk_bf16_f32 v10, v10, v11
	v_cvt_pk_bf16_f32 v11, v20, v21
	global_store_dwordx4 v[16:17], v[8:11], off nt
	s_mov_b32 s1, s20
	s_mov_b32 s0, s22
	v_pk_mul_f32 v[8:9], v[2:3], v[18:19] op_sel_hi:[1,0]
	v_pk_mul_f32 v[2:3], v[0:1], v[18:19] op_sel_hi:[1,0]
	v_pk_mul_f32 v[6:7], v[6:7], v[18:19] op_sel_hi:[1,0]
	v_pk_mul_f32 v[4:5], v[4:5], v[18:19] op_sel_hi:[1,0]
	s_nop 0
	v_cvt_pk_bf16_f32 v0, v4, v5
	v_cvt_pk_bf16_f32 v1, v6, v7
	v_cvt_pk_bf16_f32 v2, v2, v3
	v_cvt_pk_bf16_f32 v3, v8, v9
	global_store_dwordx4 v[16:17], v[0:3], off offset:256 nt
	s_cbranch_vccz .LBB0_943
	s_waitcnt vmcnt(0)
	s_cmpk_gt_u32 s33, 0xff
	s_cbranch_scc1 .LBB0_950
	s_barrier
